# hand-off version with the six LDS-DMA pieces of the heavy load phases issued before that phase's eight ds_reads
# speedup vs baseline: 1.0047x; 1.0047x over previous
; #define PG8_STAGE(bufoff, gbase, voff) do { _Pragma("unroll") for (int _i = 0; _i < 2; ++_i) \
;         __builtin_amdgcn_global_load_lds((const unsigned*)((const char*)(gbase) + (voff)[_i]), (LAS unsigned*)(lds + (bufoff) + ldsw + _i * 8192), 16, 0, 0); } while (0)
; #define PG8_LDA(dst, b, h) do { _Pragma("unroll") for (int m = 0; m < 4; ++m) _Pragma("unroll") for (int k = 0; k < 2; ++k) dst[m][k] = *(const LAS bf16x8*)(lds + PG8_SA(b, h) + aoff + m * 2048 + k * 1024); } while (0)
; #define PG8_LDB(dst, b, h) do { _Pragma("unroll") for (int n = 0; n < 2; ++n) _Pragma("unroll") for (int k = 0; k < 2; ++k) dst[n][k] = *(const LAS bf16x8*)(lds + PG8_SB(b, h) + boff + n * 2048 + k * 1024); } while (0)
; #define PG8_MMA(ai, bj, At, Bt) do { __builtin_amdgcn_s_setprio(1); _Pragma("unroll") for (int m = 0; m < 4; ++m) _Pragma("unroll") for (int n = 0; n < 2; ++n) _Pragma("unroll") for (int k = 0; k < 2; ++k) \
;         acc[ai][bj][m][n] = __builtin_amdgcn_mfma_f32_16x16x32_bf16(Bt[n][k], At[m][k], acc[ai][bj][m][n], 0, 0, 0); __builtin_amdgcn_s_setprio(0); } while (0)
; #define PG8_WAIT_V(n) asm volatile("s_waitcnt vmcnt(" #n ")" ::: "memory")
; #define PG8_WAIT_L(n) asm volatile("s_waitcnt lgkmcnt(" #n ")" ::: "memory")
; #define PG8_BAR __builtin_amdgcn_s_barrier()
; #define PG8_SCHED __builtin_amdgcn_sched_barrier(0)
; template <class Epi, class Sched>
; __device__ __forceinline__ void gemm_phase(LAS unsigned char* lds, const int K, const Sched& S, const Epi& E) {
;     ...
;             const bool last = (t == nt - 2);
;             const char* a1 = cA + (size_t)(t + 1) * kstep;
;             const char* a2 = last ? nA : cA + (size_t)(t + 2) * kstep; const char* b2 = last ? nB : cB + (size_t)(t + 2) * kstep;
;             const char* a3 = a2 + kstep; const char* b3 = b2 + kstep;
;             PG8_LDB(B0, 0, 0); PG8_LDB(B1, 0, 1); PG8_SCHED; PG8_LDA(At, 0, 0); PG8_STAGE(PG8_SA(1, 1), a1 + hstep, voffA);
;             PG8_WAIT_V(8); PG8_WAIT_L(0); PG8_BAR; PG8_MMA(0, 0, At, B0); PG8_MMA(0, 1, At, B1); PG8_BAR; PG8_SCHED;
;             PG8_LDA(At, 0, 1); PG8_STAGE(PG8_SB(0, 0), b2, voffB); PG8_STAGE(PG8_SB(0, 1), b2 + hstep, voffB); PG8_STAGE(PG8_SA(0, 0), a2, voffA);
;             PG8_WAIT_V(8); PG8_WAIT_L(0); PG8_BAR; PG8_MMA(1, 0, At, B0); PG8_MMA(1, 1, At, B1); PG8_BAR; PG8_SCHED;
.LBB0_403:
	s_add_u32 s14, s8, 0xfffc0080
	s_addc_u32 s15, s9, -1
	s_add_i32 s16, 0, 0x10000
	s_cmp_eq_u32 s13, 12
	s_cselect_b32 s55, s2, s15
	s_cselect_b32 s54, s4, s14
	v_add_u32_e32 v128, s16, v149
	s_cselect_b32 s39, s5, s12
	s_cselect_b32 s38, s10, s11
	s_add_i32 s17, 0, 0x14000
	ds_read_b128 v[158:161], v128
	ds_read_b128 v[162:165], v128 offset:1024
	ds_read_b128 v[184:187], v128 offset:2048
	ds_read_b128 v[188:191], v128 offset:3072
	v_add_u32_e32 v128, s17, v149
	ds_read_b128 v[192:195], v128
	ds_read_b128 v[196:199], v128 offset:1024
	ds_read_b128 v[200:203], v128 offset:2048
	ds_read_b128 v[204:207], v128 offset:3072
	v_lshl_add_u64 v[166:167], s[8:9], 0, v[154:155]
	s_add_i32 m0, s59, 0xc000
	ds_read_b128 v[208:211], v147
	ds_read_b128 v[212:215], v147 offset:1024
	ds_read_b128 v[216:219], v147 offset:2048
	ds_read_b128 v[220:223], v147 offset:3072
	ds_read_b128 v[224:227], v147 offset:4096
	ds_read_b128 v[228:231], v147 offset:5120
	ds_read_b128 v[232:235], v147 offset:6144
	ds_read_b128 v[236:239], v147 offset:7168
	global_load_lds_dwordx4 v[166:167], off
	v_lshl_add_u64 v[166:167], s[8:9], 0, v[156:157]
	s_add_i32 m0, s59, 0xe000
	s_nop 0
	global_load_lds_dwordx4 v[166:167], off
	s_waitcnt vmcnt(8)
	s_waitcnt lgkmcnt(0)
	s_setprio 1
	s_barrier
	v_mfma_f32_16x16x32_bf16 v[124:127], v[158:161], v[208:211], v[124:127]
	v_mfma_f32_16x16x32_bf16 v[120:123], v[184:187], v[208:211], v[120:123]
	v_mfma_f32_16x16x32_bf16 v[108:111], v[158:161], v[216:219], v[108:111]
	v_mfma_f32_16x16x32_bf16 v[104:107], v[184:187], v[216:219], v[104:107]
	v_mfma_f32_16x16x32_bf16 v[92:95], v[158:161], v[224:227], v[92:95]
	v_mfma_f32_16x16x32_bf16 v[88:91], v[184:187], v[224:227], v[88:91]
	v_mfma_f32_16x16x32_bf16 v[76:79], v[158:161], v[232:235], v[76:79]
	v_mfma_f32_16x16x32_bf16 v[72:75], v[184:187], v[232:235], v[72:75]
	v_mfma_f32_16x16x32_bf16 v[124:127], v[162:165], v[212:215], v[124:127]
	v_mfma_f32_16x16x32_bf16 v[120:123], v[188:191], v[212:215], v[120:123]
	v_mfma_f32_16x16x32_bf16 v[108:111], v[162:165], v[220:223], v[108:111]
	v_mfma_f32_16x16x32_bf16 v[104:107], v[188:191], v[220:223], v[104:107]
	v_mfma_f32_16x16x32_bf16 v[92:95], v[162:165], v[228:231], v[92:95]
	v_mfma_f32_16x16x32_bf16 v[88:91], v[188:191], v[228:231], v[88:91]
	v_mfma_f32_16x16x32_bf16 v[76:79], v[162:165], v[236:239], v[76:79]
	v_mfma_f32_16x16x32_bf16 v[72:75], v[188:191], v[236:239], v[72:75]
	s_setprio 0
	s_setprio 1
	v_mfma_f32_16x16x32_bf16 v[116:119], v[192:195], v[208:211], v[116:119]
	v_mfma_f32_16x16x32_bf16 v[112:115], v[200:203], v[208:211], v[112:115]
	v_mfma_f32_16x16x32_bf16 v[100:103], v[192:195], v[216:219], v[100:103]
	v_mfma_f32_16x16x32_bf16 v[96:99], v[200:203], v[216:219], v[96:99]
	v_mfma_f32_16x16x32_bf16 v[84:87], v[192:195], v[224:227], v[84:87]
	v_mfma_f32_16x16x32_bf16 v[80:83], v[200:203], v[224:227], v[80:83]
	v_mfma_f32_16x16x32_bf16 v[68:71], v[192:195], v[232:235], v[68:71]
	v_mfma_f32_16x16x32_bf16 v[64:67], v[200:203], v[232:235], v[64:67]
	v_mfma_f32_16x16x32_bf16 v[116:119], v[196:199], v[212:215], v[116:119]
	v_mfma_f32_16x16x32_bf16 v[112:115], v[204:207], v[212:215], v[112:115]
	v_mfma_f32_16x16x32_bf16 v[100:103], v[196:199], v[220:223], v[100:103]
	v_mfma_f32_16x16x32_bf16 v[96:99], v[204:207], v[220:223], v[96:99]
	v_mfma_f32_16x16x32_bf16 v[84:87], v[196:199], v[228:231], v[84:87]
	v_mfma_f32_16x16x32_bf16 v[80:83], v[204:207], v[228:231], v[80:83]
	v_mfma_f32_16x16x32_bf16 v[68:71], v[196:199], v[236:239], v[68:71]
	v_mfma_f32_16x16x32_bf16 v[64:67], v[204:207], v[236:239], v[64:67]
	s_barrier
	s_setprio 0
	s_add_i32 s14, s16, s58
	v_lshl_add_u64 v[166:167], s[38:39], 0, v[140:141]
	s_mov_b32 m0, s14
	s_nop 0
	global_load_lds_dwordx4 v[166:167], off
	s_add_i32 m0, s14, 0x2000
	s_add_u32 s14, s38, 0x40000
	v_lshl_add_u64 v[180:181], s[38:39], 0, v[144:145]
	s_addc_u32 s15, s39, 0
	s_add_i32 s16, s17, s58
	global_load_lds_dwordx4 v[180:181], off
	v_lshl_add_u64 v[182:183], s[14:15], 0, v[140:141]
	s_mov_b32 m0, s16
	v_lshl_add_u64 v[240:241], s[54:55], 0, v[142:143]
	global_load_lds_dwordx4 v[182:183], off
	v_lshl_add_u64 v[182:183], s[14:15], 0, v[144:145]
	s_add_i32 m0, s16, 0x2000
	s_nop 0
	global_load_lds_dwordx4 v[182:183], off
	v_lshl_add_u64 v[182:183], s[54:55], 0, v[138:139]
	s_mov_b32 m0, s59
	s_nop 0
	global_load_lds_dwordx4 v[182:183], off
	s_mov_b32 m0, s60
	s_nop 0
	global_load_lds_dwordx4 v[240:241], off
	ds_read_b128 v[208:211], v147 offset:16384
	ds_read_b128 v[212:215], v147 offset:17408
	ds_read_b128 v[216:219], v147 offset:18432
	ds_read_b128 v[220:223], v147 offset:19456
	ds_read_b128 v[224:227], v147 offset:20480
	ds_read_b128 v[228:231], v147 offset:21504
	ds_read_b128 v[232:235], v147 offset:22528
	ds_read_b128 v[236:239], v147 offset:23552
	s_waitcnt vmcnt(8)
	s_waitcnt lgkmcnt(0)
	s_setprio 1
	s_barrier
; #define PG8_STAGE(bufoff, gbase, voff) do { _Pragma("unroll") for (int _i = 0; _i < 2; ++_i) \
;         __builtin_amdgcn_global_load_lds((const unsigned*)((const char*)(gbase) + (voff)[_i]), (LAS unsigned*)(lds + (bufoff) + ldsw + _i * 8192), 16, 0, 0); } while (0)
; #define PG8_LDA(dst, b, h) do { _Pragma("unroll") for (int m = 0; m < 4; ++m) _Pragma("unroll") for (int k = 0; k < 2; ++k) dst[m][k] = *(const LAS bf16x8*)(lds + PG8_SA(b, h) + aoff + m * 2048 + k * 1024); } while (0)
; #define PG8_LDB(dst, b, h) do { _Pragma("unroll") for (int n = 0; n < 2; ++n) _Pragma("unroll") for (int k = 0; k < 2; ++k) dst[n][k] = *(const LAS bf16x8*)(lds + PG8_SB(b, h) + boff + n * 2048 + k * 1024); } while (0)
; #define PG8_MMA(ai, bj, At, Bt) do { __builtin_amdgcn_s_setprio(1); _Pragma("unroll") for (int m = 0; m < 4; ++m) _Pragma("unroll") for (int n = 0; n < 2; ++n) _Pragma("unroll") for (int k = 0; k < 2; ++k) \
;         acc[ai][bj][m][n] = __builtin_amdgcn_mfma_f32_16x16x32_bf16(Bt[n][k], At[m][k], acc[ai][bj][m][n], 0, 0, 0); __builtin_amdgcn_s_setprio(0); } while (0)
; #define PG8_WAIT_V(n) asm volatile("s_waitcnt vmcnt(" #n ")" ::: "memory")
; #define PG8_WAIT_L(n) asm volatile("s_waitcnt lgkmcnt(" #n ")" ::: "memory")
; #define PG8_BAR __builtin_amdgcn_s_barrier()
; #define PG8_SCHED __builtin_amdgcn_sched_barrier(0)
; template <class Epi, class Sched>
; __device__ __forceinline__ void gemm_phase(LAS unsigned char* lds, const int K, const Sched& S, const Epi& E) {
;     ...
;             PG8_WAIT_V(8); PG8_WAIT_L(0); PG8_BAR; PG8_MMA(1, 0, At, B0); PG8_MMA(1, 1, At, B1); PG8_BAR; PG8_SCHED;
;             PG8_LDB(B0, 1, 0); PG8_LDB(B1, 1, 1); PG8_SCHED; PG8_LDA(At, 1, 0); PG8_STAGE(PG8_SA(0, 1), a2 + hstep, voffA);
;             PG8_WAIT_V(8); PG8_WAIT_L(0); PG8_BAR; PG8_MMA(0, 0, At, B0); PG8_MMA(0, 1, At, B1); PG8_BAR; PG8_SCHED;
	v_mfma_f32_16x16x32_bf16 v[60:63], v[158:161], v[208:211], v[60:63]
	v_mfma_f32_16x16x32_bf16 v[56:59], v[184:187], v[208:211], v[56:59]
	v_mfma_f32_16x16x32_bf16 v[44:47], v[158:161], v[216:219], v[44:47]
	v_mfma_f32_16x16x32_bf16 v[40:43], v[184:187], v[216:219], v[40:43]
	v_mfma_f32_16x16x32_bf16 v[28:31], v[158:161], v[224:227], v[28:31]
	v_mfma_f32_16x16x32_bf16 v[24:27], v[184:187], v[224:227], v[24:27]
	v_mfma_f32_16x16x32_bf16 v[12:15], v[158:161], v[232:235], v[12:15]
	v_mfma_f32_16x16x32_bf16 v[8:11], v[184:187], v[232:235], v[8:11]
	v_mfma_f32_16x16x32_bf16 v[60:63], v[162:165], v[212:215], v[60:63]
	v_mfma_f32_16x16x32_bf16 v[56:59], v[188:191], v[212:215], v[56:59]
	v_mfma_f32_16x16x32_bf16 v[44:47], v[162:165], v[220:223], v[44:47]
	v_mfma_f32_16x16x32_bf16 v[40:43], v[188:191], v[220:223], v[40:43]
	v_mfma_f32_16x16x32_bf16 v[28:31], v[162:165], v[228:231], v[28:31]
	v_mfma_f32_16x16x32_bf16 v[24:27], v[188:191], v[228:231], v[24:27]
	v_mfma_f32_16x16x32_bf16 v[12:15], v[162:165], v[236:239], v[12:15]
	v_mfma_f32_16x16x32_bf16 v[8:11], v[188:191], v[236:239], v[8:11]
	s_setprio 0
	s_setprio 1
	v_mfma_f32_16x16x32_bf16 v[52:55], v[192:195], v[208:211], v[52:55]
	v_mfma_f32_16x16x32_bf16 v[48:51], v[200:203], v[208:211], v[48:51]
	v_mfma_f32_16x16x32_bf16 v[36:39], v[192:195], v[216:219], v[36:39]
	v_mfma_f32_16x16x32_bf16 v[32:35], v[200:203], v[216:219], v[32:35]
	v_mfma_f32_16x16x32_bf16 v[20:23], v[192:195], v[224:227], v[20:23]
	v_mfma_f32_16x16x32_bf16 v[16:19], v[200:203], v[224:227], v[16:19]
	v_mfma_f32_16x16x32_bf16 v[4:7], v[192:195], v[232:235], v[4:7]
	v_mfma_f32_16x16x32_bf16 v[0:3], v[200:203], v[232:235], v[0:3]
	v_mfma_f32_16x16x32_bf16 v[52:55], v[196:199], v[212:215], v[52:55]
	v_mfma_f32_16x16x32_bf16 v[48:51], v[204:207], v[212:215], v[48:51]
	v_mfma_f32_16x16x32_bf16 v[36:39], v[196:199], v[220:223], v[36:39]
	v_mfma_f32_16x16x32_bf16 v[32:35], v[204:207], v[220:223], v[32:35]
	v_mfma_f32_16x16x32_bf16 v[20:23], v[196:199], v[228:231], v[20:23]
	v_mfma_f32_16x16x32_bf16 v[16:19], v[204:207], v[228:231], v[16:19]
	v_mfma_f32_16x16x32_bf16 v[4:7], v[196:199], v[236:239], v[4:7]
	v_mfma_f32_16x16x32_bf16 v[0:3], v[204:207], v[236:239], v[0:3]
	s_barrier
	s_setprio 0
	s_add_i32 s16, 0, 0x18000
	v_add_u32_e32 v128, s16, v149
	s_add_i32 s17, 0, 0x1c000
	ds_read_b128 v[158:161], v128
	ds_read_b128 v[162:165], v128 offset:1024
	ds_read_b128 v[184:187], v128 offset:2048
	ds_read_b128 v[188:191], v128 offset:3072
	v_add_u32_e32 v128, s17, v149
	ds_read_b128 v[192:195], v128
	ds_read_b128 v[196:199], v128 offset:1024
	ds_read_b128 v[200:203], v128 offset:2048
	ds_read_b128 v[204:207], v128 offset:3072
	s_add_u32 s14, s54, 0x40000
	s_addc_u32 s15, s55, 0
	s_mov_b32 m0, s61
	v_lshl_add_u64 v[242:243], s[14:15], 0, v[138:139]
	ds_read_b128 v[208:211], v147 offset:32768
	ds_read_b128 v[212:215], v147 offset:33792
	ds_read_b128 v[216:219], v147 offset:34816
	ds_read_b128 v[220:223], v147 offset:35840
	ds_read_b128 v[224:227], v147 offset:36864
	ds_read_b128 v[228:231], v147 offset:37888
	ds_read_b128 v[232:235], v147 offset:38912
	ds_read_b128 v[236:239], v147 offset:39936
	global_load_lds_dwordx4 v[242:243], off
	v_lshl_add_u64 v[242:243], s[14:15], 0, v[142:143]
	s_mov_b32 m0, s62
	s_nop 0
	global_load_lds_dwordx4 v[242:243], off
	s_waitcnt vmcnt(8)
	s_waitcnt lgkmcnt(0)
	s_setprio 1
	s_barrier
	v_mfma_f32_16x16x32_bf16 v[124:127], v[158:161], v[208:211], v[124:127]
	v_mfma_f32_16x16x32_bf16 v[120:123], v[184:187], v[208:211], v[120:123]
	v_mfma_f32_16x16x32_bf16 v[108:111], v[158:161], v[216:219], v[108:111]
	v_mfma_f32_16x16x32_bf16 v[104:107], v[184:187], v[216:219], v[104:107]
	v_mfma_f32_16x16x32_bf16 v[92:95], v[158:161], v[224:227], v[92:95]
	v_mfma_f32_16x16x32_bf16 v[88:91], v[184:187], v[224:227], v[88:91]
	v_mfma_f32_16x16x32_bf16 v[76:79], v[158:161], v[232:235], v[76:79]
	v_mfma_f32_16x16x32_bf16 v[72:75], v[184:187], v[232:235], v[72:75]
	v_mfma_f32_16x16x32_bf16 v[124:127], v[162:165], v[212:215], v[124:127]
	v_mfma_f32_16x16x32_bf16 v[120:123], v[188:191], v[212:215], v[120:123]
	v_mfma_f32_16x16x32_bf16 v[108:111], v[162:165], v[220:223], v[108:111]
	v_mfma_f32_16x16x32_bf16 v[104:107], v[188:191], v[220:223], v[104:107]
	v_mfma_f32_16x16x32_bf16 v[92:95], v[162:165], v[228:231], v[92:95]
	v_mfma_f32_16x16x32_bf16 v[88:91], v[188:191], v[228:231], v[88:91]
	v_mfma_f32_16x16x32_bf16 v[76:79], v[162:165], v[236:239], v[76:79]
	v_mfma_f32_16x16x32_bf16 v[72:75], v[188:191], v[236:239], v[72:75]
	s_setprio 0
	s_setprio 1
	v_mfma_f32_16x16x32_bf16 v[116:119], v[192:195], v[208:211], v[116:119]
	v_mfma_f32_16x16x32_bf16 v[112:115], v[200:203], v[208:211], v[112:115]
	v_mfma_f32_16x16x32_bf16 v[100:103], v[192:195], v[216:219], v[100:103]
	v_mfma_f32_16x16x32_bf16 v[96:99], v[200:203], v[216:219], v[96:99]
	v_mfma_f32_16x16x32_bf16 v[84:87], v[192:195], v[224:227], v[84:87]
	v_mfma_f32_16x16x32_bf16 v[80:83], v[200:203], v[224:227], v[80:83]
	v_mfma_f32_16x16x32_bf16 v[68:71], v[192:195], v[232:235], v[68:71]
	v_mfma_f32_16x16x32_bf16 v[64:67], v[200:203], v[232:235], v[64:67]
	v_mfma_f32_16x16x32_bf16 v[116:119], v[196:199], v[212:215], v[116:119]
	v_mfma_f32_16x16x32_bf16 v[112:115], v[204:207], v[212:215], v[112:115]
	v_mfma_f32_16x16x32_bf16 v[100:103], v[196:199], v[220:223], v[100:103]
	v_mfma_f32_16x16x32_bf16 v[96:99], v[204:207], v[220:223], v[96:99]
	v_mfma_f32_16x16x32_bf16 v[84:87], v[196:199], v[228:231], v[84:87]
	v_mfma_f32_16x16x32_bf16 v[80:83], v[204:207], v[228:231], v[80:83]
	v_mfma_f32_16x16x32_bf16 v[68:71], v[196:199], v[236:239], v[68:71]
	v_mfma_f32_16x16x32_bf16 v[64:67], v[204:207], v[236:239], v[64:67]
	s_barrier
; #define PG8_STAGE(bufoff, gbase, voff) do { _Pragma("unroll") for (int _i = 0; _i < 2; ++_i) \
;         __builtin_amdgcn_global_load_lds((const unsigned*)((const char*)(gbase) + (voff)[_i]), (LAS unsigned*)(lds + (bufoff) + ldsw + _i * 8192), 16, 0, 0); } while (0)
; #define PG8_LDA(dst, b, h) do { _Pragma("unroll") for (int m = 0; m < 4; ++m) _Pragma("unroll") for (int k = 0; k < 2; ++k) dst[m][k] = *(const LAS bf16x8*)(lds + PG8_SA(b, h) + aoff + m * 2048 + k * 1024); } while (0)
; #define PG8_MMA(ai, bj, At, Bt) do { __builtin_amdgcn_s_setprio(1); _Pragma("unroll") for (int m = 0; m < 4; ++m) _Pragma("unroll") for (int n = 0; n < 2; ++n) _Pragma("unroll") for (int k = 0; k < 2; ++k) \
;         acc[ai][bj][m][n] = __builtin_amdgcn_mfma_f32_16x16x32_bf16(Bt[n][k], At[m][k], acc[ai][bj][m][n], 0, 0, 0); __builtin_amdgcn_s_setprio(0); } while (0)
; #define PG8_WAIT_V(n) asm volatile("s_waitcnt vmcnt(" #n ")" ::: "memory")
; #define PG8_WAIT_L(n) asm volatile("s_waitcnt lgkmcnt(" #n ")" ::: "memory")
; #define PG8_BAR __builtin_amdgcn_s_barrier()
; #define PG8_SCHED __builtin_amdgcn_sched_barrier(0)
; template <class Epi, class Sched>
; __device__ __forceinline__ void gemm_phase(LAS unsigned char* lds, const int K, const Sched& S, const Epi& E) {
;     ...
;             PG8_LDA(At, 1, 1); PG8_STAGE(PG8_SB(1, 0), b3, voffB); PG8_STAGE(PG8_SB(1, 1), b3 + hstep, voffB); PG8_STAGE(PG8_SA(1, 0), a3, voffA);
;             PG8_WAIT_V(8); PG8_WAIT_L(0); PG8_BAR; PG8_MMA(1, 0, At, B0); PG8_MMA(1, 1, At, B1); PG8_BAR; PG8_SCHED;
;         }
;         if (wr == 0) PG8_BAR;
	s_setprio 0
	s_add_i32 s14, s16, s58
	v_lshl_add_u64 v[166:167], v[166:167], 0, s[36:37]
	s_mov_b32 m0, s14
	s_nop 0
	global_load_lds_dwordx4 v[166:167], off
	s_add_i32 m0, s14, 0x2000
	s_add_u32 s14, s38, 0x40080
	v_lshl_add_u64 v[166:167], v[180:181], 0, s[36:37]
	s_addc_u32 s15, s39, 0
	s_add_i32 s16, s17, s58
	global_load_lds_dwordx4 v[166:167], off
	v_lshl_add_u64 v[166:167], s[14:15], 0, v[140:141]
	s_mov_b32 m0, s16
	s_nop 0
	global_load_lds_dwordx4 v[166:167], off
	v_lshl_add_u64 v[166:167], s[14:15], 0, v[144:145]
	s_add_i32 m0, s16, 0x2000
	s_nop 0
	global_load_lds_dwordx4 v[166:167], off
	v_lshl_add_u64 v[166:167], v[182:183], 0, s[36:37]
	s_mov_b32 m0, s64
	s_nop 0
	global_load_lds_dwordx4 v[166:167], off
	v_lshl_add_u64 v[166:167], v[240:241], 0, s[36:37]
	s_mov_b32 m0, s65
	s_nop 0
	global_load_lds_dwordx4 v[166:167], off
	ds_read_b128 v[208:211], v147 offset:49152
	ds_read_b128 v[212:215], v147 offset:50176
	ds_read_b128 v[216:219], v147 offset:51200
	ds_read_b128 v[220:223], v147 offset:52224
	ds_read_b128 v[224:227], v147 offset:53248
	ds_read_b128 v[228:231], v147 offset:54272
	ds_read_b128 v[232:235], v147 offset:55296
	ds_read_b128 v[236:239], v147 offset:56320
	s_waitcnt vmcnt(8)
	s_waitcnt lgkmcnt(0)
	s_setprio 1
	s_barrier
	v_mfma_f32_16x16x32_bf16 v[60:63], v[158:161], v[208:211], v[60:63]
	v_mfma_f32_16x16x32_bf16 v[56:59], v[184:187], v[208:211], v[56:59]
	v_mfma_f32_16x16x32_bf16 v[44:47], v[158:161], v[216:219], v[44:47]
	v_mfma_f32_16x16x32_bf16 v[40:43], v[184:187], v[216:219], v[40:43]
	v_mfma_f32_16x16x32_bf16 v[28:31], v[158:161], v[224:227], v[28:31]
	v_mfma_f32_16x16x32_bf16 v[24:27], v[184:187], v[224:227], v[24:27]
	v_mfma_f32_16x16x32_bf16 v[12:15], v[158:161], v[232:235], v[12:15]
	v_mfma_f32_16x16x32_bf16 v[8:11], v[184:187], v[232:235], v[8:11]
	v_mfma_f32_16x16x32_bf16 v[60:63], v[162:165], v[212:215], v[60:63]
	v_mfma_f32_16x16x32_bf16 v[56:59], v[188:191], v[212:215], v[56:59]
	v_mfma_f32_16x16x32_bf16 v[44:47], v[162:165], v[220:223], v[44:47]
	v_mfma_f32_16x16x32_bf16 v[40:43], v[188:191], v[220:223], v[40:43]
	v_mfma_f32_16x16x32_bf16 v[28:31], v[162:165], v[228:231], v[28:31]
	v_mfma_f32_16x16x32_bf16 v[24:27], v[188:191], v[228:231], v[24:27]
	v_mfma_f32_16x16x32_bf16 v[12:15], v[162:165], v[236:239], v[12:15]
	v_mfma_f32_16x16x32_bf16 v[8:11], v[188:191], v[236:239], v[8:11]
	s_setprio 0
	s_setprio 1
	v_mfma_f32_16x16x32_bf16 v[52:55], v[192:195], v[208:211], v[52:55]
	v_mfma_f32_16x16x32_bf16 v[48:51], v[200:203], v[208:211], v[48:51]
	v_mfma_f32_16x16x32_bf16 v[36:39], v[192:195], v[216:219], v[36:39]
	v_mfma_f32_16x16x32_bf16 v[32:35], v[200:203], v[216:219], v[32:35]
	v_mfma_f32_16x16x32_bf16 v[20:23], v[192:195], v[224:227], v[20:23]
	v_mfma_f32_16x16x32_bf16 v[16:19], v[200:203], v[224:227], v[16:19]
	v_mfma_f32_16x16x32_bf16 v[4:7], v[192:195], v[232:235], v[4:7]
	v_mfma_f32_16x16x32_bf16 v[0:3], v[200:203], v[232:235], v[0:3]
	v_mfma_f32_16x16x32_bf16 v[52:55], v[196:199], v[212:215], v[52:55]
	v_mfma_f32_16x16x32_bf16 v[48:51], v[204:207], v[212:215], v[48:51]
	v_mfma_f32_16x16x32_bf16 v[36:39], v[196:199], v[220:223], v[36:39]
	v_mfma_f32_16x16x32_bf16 v[32:35], v[204:207], v[220:223], v[32:35]
	v_mfma_f32_16x16x32_bf16 v[20:23], v[196:199], v[228:231], v[20:23]
	v_mfma_f32_16x16x32_bf16 v[16:19], v[204:207], v[228:231], v[16:19]
	v_mfma_f32_16x16x32_bf16 v[4:7], v[196:199], v[236:239], v[4:7]
	v_mfma_f32_16x16x32_bf16 v[0:3], v[204:207], v[236:239], v[0:3]
	s_barrier
	s_setprio 0
	s_add_i32 s13, s13, 2
	s_add_u32 s8, s8, 0x100
	s_addc_u32 s9, s9, 0
	s_add_u32 s11, s11, 0x100
	s_addc_u32 s12, s12, 0
	s_cmp_gt_u32 s13, 13
	s_cbranch_scc0 .LBB0_403
	s_and_b64 vcc, exec, s[42:43]
	s_cbranch_vccz .LBB0_406
	s_barrier

; #define PG8_STAGE(bufoff, gbase, voff) do { _Pragma("unroll") for (int _i = 0; _i < 2; ++_i) \
;         __builtin_amdgcn_global_load_lds((const unsigned*)((const char*)(gbase) + (voff)[_i]), (LAS unsigned*)(lds + (bufoff) + ldsw + _i * 8192), 16, 0, 0); } while (0)
; #define PG8_LDA(dst, b, h) do { _Pragma("unroll") for (int m = 0; m < 4; ++m) _Pragma("unroll") for (int k = 0; k < 2; ++k) dst[m][k] = *(const LAS bf16x8*)(lds + PG8_SA(b, h) + aoff + m * 2048 + k * 1024); } while (0)
; #define PG8_LDB(dst, b, h) do { _Pragma("unroll") for (int n = 0; n < 2; ++n) _Pragma("unroll") for (int k = 0; k < 2; ++k) dst[n][k] = *(const LAS bf16x8*)(lds + PG8_SB(b, h) + boff + n * 2048 + k * 1024); } while (0)
; #define PG8_MMA(ai, bj, At, Bt) do { __builtin_amdgcn_s_setprio(1); _Pragma("unroll") for (int m = 0; m < 4; ++m) _Pragma("unroll") for (int n = 0; n < 2; ++n) _Pragma("unroll") for (int k = 0; k < 2; ++k) \
;         acc[ai][bj][m][n] = __builtin_amdgcn_mfma_f32_16x16x32_bf16(Bt[n][k], At[m][k], acc[ai][bj][m][n], 0, 0, 0); __builtin_amdgcn_s_setprio(0); } while (0)
; #define PG8_WAIT_V(n) asm volatile("s_waitcnt vmcnt(" #n ")" ::: "memory")
; #define PG8_WAIT_L(n) asm volatile("s_waitcnt lgkmcnt(" #n ")" ::: "memory")
; #define PG8_BAR __builtin_amdgcn_s_barrier()
; #define PG8_SCHED __builtin_amdgcn_sched_barrier(0)
; template <class Epi, class Sched>
; __device__ __forceinline__ void gemm_phase(LAS unsigned char* lds, const int K, const Sched& S, const Epi& E) {
;     ...
;             const bool last = (t == nt - 2);
;             const char* a1 = cA + (size_t)(t + 1) * kstep;
;             const char* a2 = last ? nA : cA + (size_t)(t + 2) * kstep; const char* b2 = last ? nB : cB + (size_t)(t + 2) * kstep;
;             const char* a3 = a2 + kstep; const char* b3 = b2 + kstep;
;             PG8_LDB(B0, 0, 0); PG8_LDB(B1, 0, 1); PG8_SCHED; PG8_LDA(At, 0, 0); PG8_STAGE(PG8_SA(1, 1), a1 + hstep, voffA);
;             PG8_WAIT_V(8); PG8_WAIT_L(0); PG8_BAR; PG8_MMA(0, 0, At, B0); PG8_MMA(0, 1, At, B1); PG8_BAR; PG8_SCHED;
;             PG8_LDA(At, 0, 1); PG8_STAGE(PG8_SB(0, 0), b2, voffB); PG8_STAGE(PG8_SB(0, 1), b2 + hstep, voffB); PG8_STAGE(PG8_SA(0, 0), a2, voffA);
;             PG8_WAIT_V(8); PG8_WAIT_L(0); PG8_BAR; PG8_MMA(1, 0, At, B0); PG8_MMA(1, 1, At, B1); PG8_BAR; PG8_SCHED;
.LBB0_511:
	s_add_i32 s14, s8, 0xfaf9e080
	s_cmp_lg_u32 s13, 60
	s_cselect_b32 s14, s14, 0
	s_add_u32 s40, s28, s14
	s_addc_u32 s41, s29, 0
	s_add_i32 s15, 0, 0x10000
	s_add_u32 s38, s34, s14
	s_addc_u32 s39, s35, 0
	s_add_i32 s16, 0, 0x14000
	v_add_u32_e32 v164, s15, v145
	v_add_u32_e32 v180, s16, v145
	ds_read_b128 v[152:155], v164
	ds_read_b128 v[156:159], v164 offset:1024
	ds_read_b128 v[160:163], v164 offset:2048
	ds_read_b128 v[164:167], v164 offset:3072
	ds_read_b128 v[184:187], v180
	ds_read_b128 v[188:191], v180 offset:1024
	ds_read_b128 v[192:195], v180 offset:2048
	ds_read_b128 v[196:199], v180 offset:3072
	v_lshl_add_u64 v[180:181], v[146:147], 0, s[8:9]
	s_add_i32 m0, s2, 0xc000
	ds_read_b128 v[200:203], v151
	ds_read_b128 v[204:207], v151 offset:1024
	ds_read_b128 v[208:211], v151 offset:2048
	ds_read_b128 v[212:215], v151 offset:3072
	ds_read_b128 v[216:219], v151 offset:4096
	ds_read_b128 v[220:223], v151 offset:5120
	ds_read_b128 v[224:227], v151 offset:6144
	ds_read_b128 v[228:231], v151 offset:7168
	global_load_lds_dwordx4 v[180:181], off
	v_lshl_add_u64 v[180:181], v[148:149], 0, s[8:9]
	s_add_i32 m0, s2, 0xe000
	s_nop 0
	global_load_lds_dwordx4 v[180:181], off
	s_waitcnt vmcnt(8)
	s_waitcnt lgkmcnt(0)
	s_setprio 1
	s_barrier
	v_mfma_f32_16x16x32_bf16 v[124:127], v[152:155], v[200:203], v[124:127]
	v_mfma_f32_16x16x32_bf16 v[120:123], v[160:163], v[200:203], v[120:123]
	v_mfma_f32_16x16x32_bf16 v[108:111], v[152:155], v[208:211], v[108:111]
	v_mfma_f32_16x16x32_bf16 v[104:107], v[160:163], v[208:211], v[104:107]
	v_mfma_f32_16x16x32_bf16 v[92:95], v[152:155], v[216:219], v[92:95]
	v_mfma_f32_16x16x32_bf16 v[88:91], v[160:163], v[216:219], v[88:91]
	v_mfma_f32_16x16x32_bf16 v[76:79], v[152:155], v[224:227], v[76:79]
	v_mfma_f32_16x16x32_bf16 v[72:75], v[160:163], v[224:227], v[72:75]
	v_mfma_f32_16x16x32_bf16 v[124:127], v[156:159], v[204:207], v[124:127]
	v_mfma_f32_16x16x32_bf16 v[120:123], v[164:167], v[204:207], v[120:123]
	v_mfma_f32_16x16x32_bf16 v[108:111], v[156:159], v[212:215], v[108:111]
	v_mfma_f32_16x16x32_bf16 v[104:107], v[164:167], v[212:215], v[104:107]
	v_mfma_f32_16x16x32_bf16 v[92:95], v[156:159], v[220:223], v[92:95]
	v_mfma_f32_16x16x32_bf16 v[88:91], v[164:167], v[220:223], v[88:91]
	v_mfma_f32_16x16x32_bf16 v[76:79], v[156:159], v[228:231], v[76:79]
	v_mfma_f32_16x16x32_bf16 v[72:75], v[164:167], v[228:231], v[72:75]
	s_setprio 0
	s_setprio 1
	v_mfma_f32_16x16x32_bf16 v[116:119], v[184:187], v[200:203], v[116:119]
	v_mfma_f32_16x16x32_bf16 v[112:115], v[192:195], v[200:203], v[112:115]
	v_mfma_f32_16x16x32_bf16 v[100:103], v[184:187], v[208:211], v[100:103]
	v_mfma_f32_16x16x32_bf16 v[96:99], v[192:195], v[208:211], v[96:99]
	v_mfma_f32_16x16x32_bf16 v[84:87], v[184:187], v[216:219], v[84:87]
	v_mfma_f32_16x16x32_bf16 v[80:83], v[192:195], v[216:219], v[80:83]
	v_mfma_f32_16x16x32_bf16 v[68:71], v[184:187], v[224:227], v[68:71]
	v_mfma_f32_16x16x32_bf16 v[64:67], v[192:195], v[224:227], v[64:67]
	v_mfma_f32_16x16x32_bf16 v[116:119], v[188:191], v[204:207], v[116:119]
	v_mfma_f32_16x16x32_bf16 v[112:115], v[196:199], v[204:207], v[112:115]
	v_mfma_f32_16x16x32_bf16 v[100:103], v[188:191], v[212:215], v[100:103]
	v_mfma_f32_16x16x32_bf16 v[96:99], v[196:199], v[212:215], v[96:99]
	v_mfma_f32_16x16x32_bf16 v[84:87], v[188:191], v[220:223], v[84:87]
	v_mfma_f32_16x16x32_bf16 v[80:83], v[196:199], v[220:223], v[80:83]
	v_mfma_f32_16x16x32_bf16 v[68:71], v[188:191], v[228:231], v[68:71]
	v_mfma_f32_16x16x32_bf16 v[64:67], v[196:199], v[228:231], v[64:67]
	s_barrier
	s_setprio 0
	s_add_i32 s14, s15, s1
	v_lshl_add_u64 v[180:181], s[38:39], 0, v[128:129]
	s_mov_b32 m0, s14
	s_nop 0
	global_load_lds_dwordx4 v[180:181], off
	s_add_i32 m0, s14, 0x2000
	s_add_u32 s14, s38, 0x100000
	v_lshl_add_u64 v[182:183], s[38:39], 0, v[138:139]
	s_addc_u32 s15, s39, 0
	s_add_i32 s16, s16, s1
	global_load_lds_dwordx4 v[182:183], off
	v_lshl_add_u64 v[232:233], s[14:15], 0, v[128:129]
	s_mov_b32 m0, s16
	v_lshl_add_u64 v[234:235], s[40:41], 0, v[140:141]
	global_load_lds_dwordx4 v[232:233], off
	v_lshl_add_u64 v[232:233], s[14:15], 0, v[138:139]
	s_add_i32 m0, s16, 0x2000
	s_nop 0
	global_load_lds_dwordx4 v[232:233], off
	v_lshl_add_u64 v[232:233], s[40:41], 0, v[142:143]
	s_mov_b32 m0, s2
	s_nop 0
	global_load_lds_dwordx4 v[232:233], off
	s_mov_b32 m0, s3
	s_nop 0
	global_load_lds_dwordx4 v[234:235], off
	ds_read_b128 v[200:203], v151 offset:16384
	ds_read_b128 v[204:207], v151 offset:17408
	ds_read_b128 v[208:211], v151 offset:18432
	ds_read_b128 v[212:215], v151 offset:19456
	ds_read_b128 v[216:219], v151 offset:20480
	ds_read_b128 v[220:223], v151 offset:21504
	ds_read_b128 v[224:227], v151 offset:22528
	ds_read_b128 v[228:231], v151 offset:23552
	s_waitcnt vmcnt(8)
	s_waitcnt lgkmcnt(0)
	s_setprio 1
	s_barrier
; #define PG8_STAGE(bufoff, gbase, voff) do { _Pragma("unroll") for (int _i = 0; _i < 2; ++_i) \
;         __builtin_amdgcn_global_load_lds((const unsigned*)((const char*)(gbase) + (voff)[_i]), (LAS unsigned*)(lds + (bufoff) + ldsw + _i * 8192), 16, 0, 0); } while (0)
; #define PG8_LDA(dst, b, h) do { _Pragma("unroll") for (int m = 0; m < 4; ++m) _Pragma("unroll") for (int k = 0; k < 2; ++k) dst[m][k] = *(const LAS bf16x8*)(lds + PG8_SA(b, h) + aoff + m * 2048 + k * 1024); } while (0)
; #define PG8_LDB(dst, b, h) do { _Pragma("unroll") for (int n = 0; n < 2; ++n) _Pragma("unroll") for (int k = 0; k < 2; ++k) dst[n][k] = *(const LAS bf16x8*)(lds + PG8_SB(b, h) + boff + n * 2048 + k * 1024); } while (0)
; #define PG8_MMA(ai, bj, At, Bt) do { __builtin_amdgcn_s_setprio(1); _Pragma("unroll") for (int m = 0; m < 4; ++m) _Pragma("unroll") for (int n = 0; n < 2; ++n) _Pragma("unroll") for (int k = 0; k < 2; ++k) \
;         acc[ai][bj][m][n] = __builtin_amdgcn_mfma_f32_16x16x32_bf16(Bt[n][k], At[m][k], acc[ai][bj][m][n], 0, 0, 0); __builtin_amdgcn_s_setprio(0); } while (0)
; #define PG8_WAIT_V(n) asm volatile("s_waitcnt vmcnt(" #n ")" ::: "memory")
; #define PG8_WAIT_L(n) asm volatile("s_waitcnt lgkmcnt(" #n ")" ::: "memory")
; #define PG8_BAR __builtin_amdgcn_s_barrier()
; #define PG8_SCHED __builtin_amdgcn_sched_barrier(0)
; template <class Epi, class Sched>
; __device__ __forceinline__ void gemm_phase(LAS unsigned char* lds, const int K, const Sched& S, const Epi& E) {
;     ...
;             PG8_WAIT_V(8); PG8_WAIT_L(0); PG8_BAR; PG8_MMA(1, 0, At, B0); PG8_MMA(1, 1, At, B1); PG8_BAR; PG8_SCHED;
;             PG8_LDB(B0, 1, 0); PG8_LDB(B1, 1, 1); PG8_SCHED; PG8_LDA(At, 1, 0); PG8_STAGE(PG8_SA(0, 1), a2 + hstep, voffA);
;             PG8_WAIT_V(8); PG8_WAIT_L(0); PG8_BAR; PG8_MMA(0, 0, At, B0); PG8_MMA(0, 1, At, B1); PG8_BAR; PG8_SCHED;
	v_mfma_f32_16x16x32_bf16 v[60:63], v[152:155], v[200:203], v[60:63]
	v_mfma_f32_16x16x32_bf16 v[56:59], v[160:163], v[200:203], v[56:59]
	v_mfma_f32_16x16x32_bf16 v[44:47], v[152:155], v[208:211], v[44:47]
	v_mfma_f32_16x16x32_bf16 v[40:43], v[160:163], v[208:211], v[40:43]
	v_mfma_f32_16x16x32_bf16 v[28:31], v[152:155], v[216:219], v[28:31]
	v_mfma_f32_16x16x32_bf16 v[24:27], v[160:163], v[216:219], v[24:27]
	v_mfma_f32_16x16x32_bf16 v[12:15], v[152:155], v[224:227], v[12:15]
	v_mfma_f32_16x16x32_bf16 v[8:11], v[160:163], v[224:227], v[8:11]
	v_mfma_f32_16x16x32_bf16 v[60:63], v[156:159], v[204:207], v[60:63]
	v_mfma_f32_16x16x32_bf16 v[56:59], v[164:167], v[204:207], v[56:59]
	v_mfma_f32_16x16x32_bf16 v[44:47], v[156:159], v[212:215], v[44:47]
	v_mfma_f32_16x16x32_bf16 v[40:43], v[164:167], v[212:215], v[40:43]
	v_mfma_f32_16x16x32_bf16 v[28:31], v[156:159], v[220:223], v[28:31]
	v_mfma_f32_16x16x32_bf16 v[24:27], v[164:167], v[220:223], v[24:27]
	v_mfma_f32_16x16x32_bf16 v[12:15], v[156:159], v[228:231], v[12:15]
	v_mfma_f32_16x16x32_bf16 v[8:11], v[164:167], v[228:231], v[8:11]
	s_setprio 0
	s_setprio 1
	v_mfma_f32_16x16x32_bf16 v[52:55], v[184:187], v[200:203], v[52:55]
	v_mfma_f32_16x16x32_bf16 v[48:51], v[192:195], v[200:203], v[48:51]
	v_mfma_f32_16x16x32_bf16 v[36:39], v[184:187], v[208:211], v[36:39]
	v_mfma_f32_16x16x32_bf16 v[32:35], v[192:195], v[208:211], v[32:35]
	v_mfma_f32_16x16x32_bf16 v[20:23], v[184:187], v[216:219], v[20:23]
	v_mfma_f32_16x16x32_bf16 v[16:19], v[192:195], v[216:219], v[16:19]
	v_mfma_f32_16x16x32_bf16 v[4:7], v[184:187], v[224:227], v[4:7]
	v_mfma_f32_16x16x32_bf16 v[0:3], v[192:195], v[224:227], v[0:3]
	v_mfma_f32_16x16x32_bf16 v[52:55], v[188:191], v[204:207], v[52:55]
	v_mfma_f32_16x16x32_bf16 v[48:51], v[196:199], v[204:207], v[48:51]
	v_mfma_f32_16x16x32_bf16 v[36:39], v[188:191], v[212:215], v[36:39]
	v_mfma_f32_16x16x32_bf16 v[32:35], v[196:199], v[212:215], v[32:35]
	v_mfma_f32_16x16x32_bf16 v[20:23], v[188:191], v[220:223], v[20:23]
	v_mfma_f32_16x16x32_bf16 v[16:19], v[196:199], v[220:223], v[16:19]
	v_mfma_f32_16x16x32_bf16 v[4:7], v[188:191], v[228:231], v[4:7]
	v_mfma_f32_16x16x32_bf16 v[0:3], v[196:199], v[228:231], v[0:3]
	s_barrier
	s_setprio 0
	s_add_i32 s16, 0, 0x18000
	s_add_i32 s17, 0, 0x1c000
	v_add_u32_e32 v164, s16, v145
	v_add_u32_e32 v196, s17, v145
	ds_read_b128 v[152:155], v164
	ds_read_b128 v[156:159], v164 offset:1024
	ds_read_b128 v[160:163], v164 offset:2048
	ds_read_b128 v[164:167], v164 offset:3072
	ds_read_b128 v[184:187], v196
	ds_read_b128 v[188:191], v196 offset:1024
	ds_read_b128 v[192:195], v196 offset:2048
	ds_read_b128 v[196:199], v196 offset:3072
	s_add_u32 s14, s40, 0x100000
	s_addc_u32 s15, s41, 0
	s_mov_b32 m0, s4
	v_lshl_add_u64 v[236:237], s[14:15], 0, v[142:143]
	ds_read_b128 v[200:203], v151 offset:32768
	ds_read_b128 v[204:207], v151 offset:33792
	ds_read_b128 v[208:211], v151 offset:34816
	ds_read_b128 v[212:215], v151 offset:35840
	ds_read_b128 v[216:219], v151 offset:36864
	ds_read_b128 v[220:223], v151 offset:37888
	ds_read_b128 v[224:227], v151 offset:38912
	ds_read_b128 v[228:231], v151 offset:39936
	global_load_lds_dwordx4 v[236:237], off
	v_lshl_add_u64 v[236:237], s[14:15], 0, v[140:141]
	s_mov_b32 m0, s5
	s_nop 0
	global_load_lds_dwordx4 v[236:237], off
	s_waitcnt vmcnt(8)
	s_waitcnt lgkmcnt(0)
	s_setprio 1
	s_barrier
	v_mfma_f32_16x16x32_bf16 v[124:127], v[152:155], v[200:203], v[124:127]
	v_mfma_f32_16x16x32_bf16 v[120:123], v[160:163], v[200:203], v[120:123]
	v_mfma_f32_16x16x32_bf16 v[108:111], v[152:155], v[208:211], v[108:111]
	v_mfma_f32_16x16x32_bf16 v[104:107], v[160:163], v[208:211], v[104:107]
	v_mfma_f32_16x16x32_bf16 v[92:95], v[152:155], v[216:219], v[92:95]
	v_mfma_f32_16x16x32_bf16 v[88:91], v[160:163], v[216:219], v[88:91]
	v_mfma_f32_16x16x32_bf16 v[76:79], v[152:155], v[224:227], v[76:79]
	v_mfma_f32_16x16x32_bf16 v[72:75], v[160:163], v[224:227], v[72:75]
	v_mfma_f32_16x16x32_bf16 v[124:127], v[156:159], v[204:207], v[124:127]
	v_mfma_f32_16x16x32_bf16 v[120:123], v[164:167], v[204:207], v[120:123]
	v_mfma_f32_16x16x32_bf16 v[108:111], v[156:159], v[212:215], v[108:111]
	v_mfma_f32_16x16x32_bf16 v[104:107], v[164:167], v[212:215], v[104:107]
	v_mfma_f32_16x16x32_bf16 v[92:95], v[156:159], v[220:223], v[92:95]
	v_mfma_f32_16x16x32_bf16 v[88:91], v[164:167], v[220:223], v[88:91]
	v_mfma_f32_16x16x32_bf16 v[76:79], v[156:159], v[228:231], v[76:79]
	v_mfma_f32_16x16x32_bf16 v[72:75], v[164:167], v[228:231], v[72:75]
	s_setprio 0
	s_setprio 1
	v_mfma_f32_16x16x32_bf16 v[116:119], v[184:187], v[200:203], v[116:119]
	v_mfma_f32_16x16x32_bf16 v[112:115], v[192:195], v[200:203], v[112:115]
	v_mfma_f32_16x16x32_bf16 v[100:103], v[184:187], v[208:211], v[100:103]
	v_mfma_f32_16x16x32_bf16 v[96:99], v[192:195], v[208:211], v[96:99]
	v_mfma_f32_16x16x32_bf16 v[84:87], v[184:187], v[216:219], v[84:87]
	v_mfma_f32_16x16x32_bf16 v[80:83], v[192:195], v[216:219], v[80:83]
	v_mfma_f32_16x16x32_bf16 v[68:71], v[184:187], v[224:227], v[68:71]
	v_mfma_f32_16x16x32_bf16 v[64:67], v[192:195], v[224:227], v[64:67]
	v_mfma_f32_16x16x32_bf16 v[116:119], v[188:191], v[204:207], v[116:119]
	v_mfma_f32_16x16x32_bf16 v[112:115], v[196:199], v[204:207], v[112:115]
	v_mfma_f32_16x16x32_bf16 v[100:103], v[188:191], v[212:215], v[100:103]
	v_mfma_f32_16x16x32_bf16 v[96:99], v[196:199], v[212:215], v[96:99]
	v_mfma_f32_16x16x32_bf16 v[84:87], v[188:191], v[220:223], v[84:87]
	v_mfma_f32_16x16x32_bf16 v[80:83], v[196:199], v[220:223], v[80:83]
	v_mfma_f32_16x16x32_bf16 v[68:71], v[188:191], v[228:231], v[68:71]
	v_mfma_f32_16x16x32_bf16 v[64:67], v[196:199], v[228:231], v[64:67]
	s_barrier
; #define PG8_STAGE(bufoff, gbase, voff) do { _Pragma("unroll") for (int _i = 0; _i < 2; ++_i) \
;         __builtin_amdgcn_global_load_lds((const unsigned*)((const char*)(gbase) + (voff)[_i]), (LAS unsigned*)(lds + (bufoff) + ldsw + _i * 8192), 16, 0, 0); } while (0)
; #define PG8_LDA(dst, b, h) do { _Pragma("unroll") for (int m = 0; m < 4; ++m) _Pragma("unroll") for (int k = 0; k < 2; ++k) dst[m][k] = *(const LAS bf16x8*)(lds + PG8_SA(b, h) + aoff + m * 2048 + k * 1024); } while (0)
; #define PG8_MMA(ai, bj, At, Bt) do { __builtin_amdgcn_s_setprio(1); _Pragma("unroll") for (int m = 0; m < 4; ++m) _Pragma("unroll") for (int n = 0; n < 2; ++n) _Pragma("unroll") for (int k = 0; k < 2; ++k) \
;         acc[ai][bj][m][n] = __builtin_amdgcn_mfma_f32_16x16x32_bf16(Bt[n][k], At[m][k], acc[ai][bj][m][n], 0, 0, 0); __builtin_amdgcn_s_setprio(0); } while (0)
; #define PG8_WAIT_V(n) asm volatile("s_waitcnt vmcnt(" #n ")" ::: "memory")
; #define PG8_WAIT_L(n) asm volatile("s_waitcnt lgkmcnt(" #n ")" ::: "memory")
; #define PG8_BAR __builtin_amdgcn_s_barrier()
; #define PG8_SCHED __builtin_amdgcn_sched_barrier(0)
; template <class Epi, class Sched>
; __device__ __forceinline__ void gemm_phase(LAS unsigned char* lds, const int K, const Sched& S, const Epi& E) {
;     ...
;             PG8_LDA(At, 1, 1); PG8_STAGE(PG8_SB(1, 0), b3, voffB); PG8_STAGE(PG8_SB(1, 1), b3 + hstep, voffB); PG8_STAGE(PG8_SA(1, 0), a3, voffA);
;             PG8_WAIT_V(8); PG8_WAIT_L(0); PG8_BAR; PG8_MMA(1, 0, At, B0); PG8_MMA(1, 1, At, B1); PG8_BAR; PG8_SCHED;
;         }
;         if (wr == 0) PG8_BAR;
	s_setprio 0
	s_add_i32 s14, s16, s1
	v_lshl_add_u64 v[180:181], v[180:181], 0, s[36:37]
	s_mov_b32 m0, s14
	s_nop 0
	global_load_lds_dwordx4 v[180:181], off
	s_add_i32 m0, s14, 0x2000
	s_add_u32 s14, s38, 0x100080
	v_lshl_add_u64 v[180:181], v[182:183], 0, s[36:37]
	s_addc_u32 s15, s39, 0
	s_add_i32 s16, s17, s1
	global_load_lds_dwordx4 v[180:181], off
	v_lshl_add_u64 v[180:181], s[14:15], 0, v[128:129]
	s_mov_b32 m0, s16
	s_nop 0
	global_load_lds_dwordx4 v[180:181], off
	v_lshl_add_u64 v[180:181], s[14:15], 0, v[138:139]
	s_add_i32 m0, s16, 0x2000
	s_nop 0
	global_load_lds_dwordx4 v[180:181], off
	v_lshl_add_u64 v[180:181], v[232:233], 0, s[36:37]
	s_mov_b32 m0, s11
	s_nop 0
	global_load_lds_dwordx4 v[180:181], off
	v_lshl_add_u64 v[180:181], v[234:235], 0, s[36:37]
	s_mov_b32 m0, s12
	s_nop 0
	global_load_lds_dwordx4 v[180:181], off
	ds_read_b128 v[200:203], v151 offset:49152
	ds_read_b128 v[204:207], v151 offset:50176
	ds_read_b128 v[208:211], v151 offset:51200
	ds_read_b128 v[212:215], v151 offset:52224
	ds_read_b128 v[216:219], v151 offset:53248
	ds_read_b128 v[220:223], v151 offset:54272
	ds_read_b128 v[224:227], v151 offset:55296
	ds_read_b128 v[228:231], v151 offset:56320
	s_waitcnt vmcnt(8)
	s_waitcnt lgkmcnt(0)
	s_setprio 1
	s_barrier
	v_mfma_f32_16x16x32_bf16 v[60:63], v[152:155], v[200:203], v[60:63]
	v_mfma_f32_16x16x32_bf16 v[56:59], v[160:163], v[200:203], v[56:59]
	v_mfma_f32_16x16x32_bf16 v[44:47], v[152:155], v[208:211], v[44:47]
	v_mfma_f32_16x16x32_bf16 v[40:43], v[160:163], v[208:211], v[40:43]
	v_mfma_f32_16x16x32_bf16 v[28:31], v[152:155], v[216:219], v[28:31]
	v_mfma_f32_16x16x32_bf16 v[24:27], v[160:163], v[216:219], v[24:27]
	v_mfma_f32_16x16x32_bf16 v[12:15], v[152:155], v[224:227], v[12:15]
	v_mfma_f32_16x16x32_bf16 v[8:11], v[160:163], v[224:227], v[8:11]
	v_mfma_f32_16x16x32_bf16 v[60:63], v[156:159], v[204:207], v[60:63]
	v_mfma_f32_16x16x32_bf16 v[56:59], v[164:167], v[204:207], v[56:59]
	v_mfma_f32_16x16x32_bf16 v[44:47], v[156:159], v[212:215], v[44:47]
	v_mfma_f32_16x16x32_bf16 v[40:43], v[164:167], v[212:215], v[40:43]
	v_mfma_f32_16x16x32_bf16 v[28:31], v[156:159], v[220:223], v[28:31]
	v_mfma_f32_16x16x32_bf16 v[24:27], v[164:167], v[220:223], v[24:27]
	v_mfma_f32_16x16x32_bf16 v[12:15], v[156:159], v[228:231], v[12:15]
	v_mfma_f32_16x16x32_bf16 v[8:11], v[164:167], v[228:231], v[8:11]
	s_setprio 0
	s_setprio 1
	v_mfma_f32_16x16x32_bf16 v[52:55], v[184:187], v[200:203], v[52:55]
	v_mfma_f32_16x16x32_bf16 v[48:51], v[192:195], v[200:203], v[48:51]
	v_mfma_f32_16x16x32_bf16 v[36:39], v[184:187], v[208:211], v[36:39]
	v_mfma_f32_16x16x32_bf16 v[32:35], v[192:195], v[208:211], v[32:35]
	v_mfma_f32_16x16x32_bf16 v[20:23], v[184:187], v[216:219], v[20:23]
	v_mfma_f32_16x16x32_bf16 v[16:19], v[192:195], v[216:219], v[16:19]
	v_mfma_f32_16x16x32_bf16 v[4:7], v[184:187], v[224:227], v[4:7]
	v_mfma_f32_16x16x32_bf16 v[0:3], v[192:195], v[224:227], v[0:3]
	v_mfma_f32_16x16x32_bf16 v[52:55], v[188:191], v[204:207], v[52:55]
	v_mfma_f32_16x16x32_bf16 v[48:51], v[196:199], v[204:207], v[48:51]
	v_mfma_f32_16x16x32_bf16 v[36:39], v[188:191], v[212:215], v[36:39]
	v_mfma_f32_16x16x32_bf16 v[32:35], v[196:199], v[212:215], v[32:35]
	v_mfma_f32_16x16x32_bf16 v[20:23], v[188:191], v[220:223], v[20:23]
	v_mfma_f32_16x16x32_bf16 v[16:19], v[196:199], v[220:223], v[16:19]
	v_mfma_f32_16x16x32_bf16 v[4:7], v[188:191], v[228:231], v[4:7]
	v_mfma_f32_16x16x32_bf16 v[0:3], v[196:199], v[228:231], v[0:3]
	s_barrier
	s_setprio 0
	s_add_i32 s13, s13, 2
	s_add_u32 s8, s8, 0x100
	s_addc_u32 s9, s9, 0
	s_cmp_gt_u32 s13, 61
	s_cbranch_scc0 .LBB0_511
	s_cmpk_lt_u32 s0, 0x100
	s_cbranch_scc0 .LBB0_514
	s_barrier

; #define PG8_STAGE(bufoff, gbase, voff) do { _Pragma("unroll") for (int _i = 0; _i < 2; ++_i) \
;         __builtin_amdgcn_global_load_lds((const unsigned*)((const char*)(gbase) + (voff)[_i]), (LAS unsigned*)(lds + (bufoff) + ldsw + _i * 8192), 16, 0, 0); } while (0)
; #define PG8_LDA(dst, b, h) do { _Pragma("unroll") for (int m = 0; m < 4; ++m) _Pragma("unroll") for (int k = 0; k < 2; ++k) dst[m][k] = *(const LAS bf16x8*)(lds + PG8_SA(b, h) + aoff + m * 2048 + k * 1024); } while (0)
; #define PG8_LDB(dst, b, h) do { _Pragma("unroll") for (int n = 0; n < 2; ++n) _Pragma("unroll") for (int k = 0; k < 2; ++k) dst[n][k] = *(const LAS bf16x8*)(lds + PG8_SB(b, h) + boff + n * 2048 + k * 1024); } while (0)
; #define PG8_MMA(ai, bj, At, Bt) do { __builtin_amdgcn_s_setprio(1); _Pragma("unroll") for (int m = 0; m < 4; ++m) _Pragma("unroll") for (int n = 0; n < 2; ++n) _Pragma("unroll") for (int k = 0; k < 2; ++k) \
;         acc[ai][bj][m][n] = __builtin_amdgcn_mfma_f32_16x16x32_bf16(Bt[n][k], At[m][k], acc[ai][bj][m][n], 0, 0, 0); __builtin_amdgcn_s_setprio(0); } while (0)
; #define PG8_WAIT_V(n) asm volatile("s_waitcnt vmcnt(" #n ")" ::: "memory")
; #define PG8_WAIT_L(n) asm volatile("s_waitcnt lgkmcnt(" #n ")" ::: "memory")
; #define PG8_BAR __builtin_amdgcn_s_barrier()
; #define PG8_SCHED __builtin_amdgcn_sched_barrier(0)
; template <class Epi, class Sched>
; __device__ __forceinline__ void gemm_phase(LAS unsigned char* lds, const int K, const Sched& S, const Epi& E) {
;     ...
;             const bool last = (t == nt - 2);
;             const char* a1 = cA + (size_t)(t + 1) * kstep;
;             const char* a2 = last ? nA : cA + (size_t)(t + 2) * kstep; const char* b2 = last ? nB : cB + (size_t)(t + 2) * kstep;
;             const char* a3 = a2 + kstep; const char* b3 = b2 + kstep;
;             PG8_LDB(B0, 0, 0); PG8_LDB(B1, 0, 1); PG8_SCHED; PG8_LDA(At, 0, 0); PG8_STAGE(PG8_SA(1, 1), a1 + hstep, voffA);
;             PG8_WAIT_V(8); PG8_WAIT_L(0); PG8_BAR; PG8_MMA(0, 0, At, B0); PG8_MMA(0, 1, At, B1); PG8_BAR; PG8_SCHED;
;             PG8_LDA(At, 0, 1); PG8_STAGE(PG8_SB(0, 0), b2, voffB); PG8_STAGE(PG8_SB(0, 1), b2 + hstep, voffB); PG8_STAGE(PG8_SA(0, 0), a2, voffA);
;             PG8_WAIT_V(8); PG8_WAIT_L(0); PG8_BAR; PG8_MMA(1, 0, At, B0); PG8_MMA(1, 1, At, B1); PG8_BAR; PG8_SCHED;
.LBB0_812:
	s_add_i32 s16, s15, 2
	s_add_u32 s50, s8, 0x100
	s_addc_u32 s51, s9, 0
	s_add_i32 s17, 0, 0x10000
	s_cmp_eq_u32 s12, s15
	s_cselect_b32 s55, s4, s51
	s_cselect_b32 s54, s5, s50
	s_cselect_b32 s53, s10, s14
	s_cselect_b32 s52, s11, s13
	s_add_i32 s15, 0, 0x14000
	v_add_u32_e32 v158, s17, v164
	v_add_u32_e32 v162, s15, v164
	ds_read_b128 v[146:149], v158
	ds_read_b128 v[150:153], v158 offset:1024
	ds_read_b128 v[154:157], v158 offset:2048
	ds_read_b128 v[158:161], v158 offset:3072
	ds_read_b128 v[184:187], v162
	ds_read_b128 v[188:191], v162 offset:1024
	ds_read_b128 v[192:195], v162 offset:2048
	ds_read_b128 v[196:199], v162 offset:3072
	v_lshl_add_u64 v[162:163], s[8:9], 0, v[142:143]
	s_add_i32 m0, s26, 0xc000
	ds_read_b128 v[200:203], v166
	ds_read_b128 v[204:207], v166 offset:1024
	ds_read_b128 v[208:211], v166 offset:2048
	ds_read_b128 v[212:215], v166 offset:3072
	ds_read_b128 v[216:219], v166 offset:4096
	ds_read_b128 v[220:223], v166 offset:5120
	ds_read_b128 v[224:227], v166 offset:6144
	ds_read_b128 v[228:231], v166 offset:7168
	global_load_lds_dwordx4 v[162:163], off
	v_lshl_add_u64 v[162:163], s[8:9], 0, v[144:145]
	s_add_i32 m0, s26, 0xe000
	s_nop 0
	global_load_lds_dwordx4 v[162:163], off
	s_waitcnt vmcnt(8)
	s_waitcnt lgkmcnt(0)
	s_setprio 1
	s_barrier
	v_mfma_f32_16x16x32_bf16 v[124:127], v[146:149], v[200:203], v[124:127]
	v_mfma_f32_16x16x32_bf16 v[92:95], v[154:157], v[200:203], v[92:95]
	v_mfma_f32_16x16x32_bf16 v[120:123], v[146:149], v[208:211], v[120:123]
	v_mfma_f32_16x16x32_bf16 v[88:91], v[154:157], v[208:211], v[88:91]
	v_mfma_f32_16x16x32_bf16 v[116:119], v[146:149], v[216:219], v[116:119]
	v_mfma_f32_16x16x32_bf16 v[84:87], v[154:157], v[216:219], v[84:87]
	v_mfma_f32_16x16x32_bf16 v[112:115], v[146:149], v[224:227], v[112:115]
	v_mfma_f32_16x16x32_bf16 v[80:83], v[154:157], v[224:227], v[80:83]
	v_mfma_f32_16x16x32_bf16 v[124:127], v[150:153], v[204:207], v[124:127]
	v_mfma_f32_16x16x32_bf16 v[92:95], v[158:161], v[204:207], v[92:95]
	v_mfma_f32_16x16x32_bf16 v[120:123], v[150:153], v[212:215], v[120:123]
	v_mfma_f32_16x16x32_bf16 v[88:91], v[158:161], v[212:215], v[88:91]
	v_mfma_f32_16x16x32_bf16 v[116:119], v[150:153], v[220:223], v[116:119]
	v_mfma_f32_16x16x32_bf16 v[84:87], v[158:161], v[220:223], v[84:87]
	v_mfma_f32_16x16x32_bf16 v[112:115], v[150:153], v[228:231], v[112:115]
	v_mfma_f32_16x16x32_bf16 v[80:83], v[158:161], v[228:231], v[80:83]
	s_setprio 0
	s_setprio 1
	v_mfma_f32_16x16x32_bf16 v[64:67], v[184:187], v[200:203], v[64:67]
	v_mfma_f32_16x16x32_bf16 v[40:43], v[192:195], v[200:203], v[40:43]
	v_mfma_f32_16x16x32_bf16 v[56:59], v[184:187], v[208:211], v[56:59]
	v_mfma_f32_16x16x32_bf16 v[32:35], v[192:195], v[208:211], v[32:35]
	v_mfma_f32_16x16x32_bf16 v[52:55], v[184:187], v[216:219], v[52:55]
	v_mfma_f32_16x16x32_bf16 v[24:27], v[192:195], v[216:219], v[24:27]
	v_mfma_f32_16x16x32_bf16 v[48:51], v[184:187], v[224:227], v[48:51]
	v_mfma_f32_16x16x32_bf16 v[16:19], v[192:195], v[224:227], v[16:19]
	v_mfma_f32_16x16x32_bf16 v[64:67], v[188:191], v[204:207], v[64:67]
	v_mfma_f32_16x16x32_bf16 v[40:43], v[196:199], v[204:207], v[40:43]
	v_mfma_f32_16x16x32_bf16 v[56:59], v[188:191], v[212:215], v[56:59]
	v_mfma_f32_16x16x32_bf16 v[32:35], v[196:199], v[212:215], v[32:35]
	v_mfma_f32_16x16x32_bf16 v[52:55], v[188:191], v[220:223], v[52:55]
	v_mfma_f32_16x16x32_bf16 v[24:27], v[196:199], v[220:223], v[24:27]
	v_mfma_f32_16x16x32_bf16 v[48:51], v[188:191], v[228:231], v[48:51]
	v_mfma_f32_16x16x32_bf16 v[16:19], v[196:199], v[228:231], v[16:19]
	s_barrier
	s_setprio 0
	s_add_i32 s8, s17, s3
	v_lshl_add_u64 v[162:163], s[52:53], 0, v[128:129]
	s_mov_b32 m0, s8
	s_nop 0
	global_load_lds_dwordx4 v[162:163], off
	s_add_i32 m0, s8, 0x2000
	s_add_u32 s8, s52, 0x50000
	v_lshl_add_u64 v[180:181], s[52:53], 0, v[138:139]
	s_addc_u32 s9, s53, 0
	s_add_i32 s15, s15, s3
	global_load_lds_dwordx4 v[180:181], off
	v_lshl_add_u64 v[182:183], s[8:9], 0, v[128:129]
	s_mov_b32 m0, s15
	v_lshl_add_u64 v[232:233], s[54:55], 0, v[138:139]
	global_load_lds_dwordx4 v[182:183], off
	v_lshl_add_u64 v[182:183], s[8:9], 0, v[138:139]
	s_add_i32 m0, s15, 0x2000
	s_nop 0
	global_load_lds_dwordx4 v[182:183], off
	v_lshl_add_u64 v[182:183], s[54:55], 0, v[128:129]
	s_mov_b32 m0, s26
	s_nop 0
	global_load_lds_dwordx4 v[182:183], off
	s_mov_b32 m0, s27
	s_nop 0
	global_load_lds_dwordx4 v[232:233], off
	ds_read_b128 v[200:203], v166 offset:16384
	ds_read_b128 v[204:207], v166 offset:17408
	ds_read_b128 v[208:211], v166 offset:18432
	ds_read_b128 v[212:215], v166 offset:19456
	ds_read_b128 v[216:219], v166 offset:20480
	ds_read_b128 v[220:223], v166 offset:21504
	ds_read_b128 v[224:227], v166 offset:22528
	ds_read_b128 v[228:231], v166 offset:23552
	s_waitcnt vmcnt(8)
	s_waitcnt lgkmcnt(0)
	s_setprio 1
	s_barrier
; #define PG8_STAGE(bufoff, gbase, voff) do { _Pragma("unroll") for (int _i = 0; _i < 2; ++_i) \
;         __builtin_amdgcn_global_load_lds((const unsigned*)((const char*)(gbase) + (voff)[_i]), (LAS unsigned*)(lds + (bufoff) + ldsw + _i * 8192), 16, 0, 0); } while (0)
; #define PG8_LDA(dst, b, h) do { _Pragma("unroll") for (int m = 0; m < 4; ++m) _Pragma("unroll") for (int k = 0; k < 2; ++k) dst[m][k] = *(const LAS bf16x8*)(lds + PG8_SA(b, h) + aoff + m * 2048 + k * 1024); } while (0)
; #define PG8_LDB(dst, b, h) do { _Pragma("unroll") for (int n = 0; n < 2; ++n) _Pragma("unroll") for (int k = 0; k < 2; ++k) dst[n][k] = *(const LAS bf16x8*)(lds + PG8_SB(b, h) + boff + n * 2048 + k * 1024); } while (0)
; #define PG8_MMA(ai, bj, At, Bt) do { __builtin_amdgcn_s_setprio(1); _Pragma("unroll") for (int m = 0; m < 4; ++m) _Pragma("unroll") for (int n = 0; n < 2; ++n) _Pragma("unroll") for (int k = 0; k < 2; ++k) \
;         acc[ai][bj][m][n] = __builtin_amdgcn_mfma_f32_16x16x32_bf16(Bt[n][k], At[m][k], acc[ai][bj][m][n], 0, 0, 0); __builtin_amdgcn_s_setprio(0); } while (0)
; #define PG8_WAIT_V(n) asm volatile("s_waitcnt vmcnt(" #n ")" ::: "memory")
; #define PG8_WAIT_L(n) asm volatile("s_waitcnt lgkmcnt(" #n ")" ::: "memory")
; #define PG8_BAR __builtin_amdgcn_s_barrier()
; #define PG8_SCHED __builtin_amdgcn_sched_barrier(0)
; template <class Epi, class Sched>
; __device__ __forceinline__ void gemm_phase(LAS unsigned char* lds, const int K, const Sched& S, const Epi& E) {
;     ...
;             PG8_WAIT_V(8); PG8_WAIT_L(0); PG8_BAR; PG8_MMA(1, 0, At, B0); PG8_MMA(1, 1, At, B1); PG8_BAR; PG8_SCHED;
;             PG8_LDB(B0, 1, 0); PG8_LDB(B1, 1, 1); PG8_SCHED; PG8_LDA(At, 1, 0); PG8_STAGE(PG8_SA(0, 1), a2 + hstep, voffA);
;             PG8_WAIT_V(8); PG8_WAIT_L(0); PG8_BAR; PG8_MMA(0, 0, At, B0); PG8_MMA(0, 1, At, B1); PG8_BAR; PG8_SCHED;
	v_mfma_f32_16x16x32_bf16 v[108:111], v[146:149], v[200:203], v[108:111]
	v_mfma_f32_16x16x32_bf16 v[76:79], v[154:157], v[200:203], v[76:79]
	v_mfma_f32_16x16x32_bf16 v[104:107], v[146:149], v[208:211], v[104:107]
	v_mfma_f32_16x16x32_bf16 v[72:75], v[154:157], v[208:211], v[72:75]
	v_mfma_f32_16x16x32_bf16 v[100:103], v[146:149], v[216:219], v[100:103]
	v_mfma_f32_16x16x32_bf16 v[68:71], v[154:157], v[216:219], v[68:71]
	v_mfma_f32_16x16x32_bf16 v[96:99], v[146:149], v[224:227], v[96:99]
	v_mfma_f32_16x16x32_bf16 v[60:63], v[154:157], v[224:227], v[60:63]
	v_mfma_f32_16x16x32_bf16 v[108:111], v[150:153], v[204:207], v[108:111]
	v_mfma_f32_16x16x32_bf16 v[76:79], v[158:161], v[204:207], v[76:79]
	v_mfma_f32_16x16x32_bf16 v[104:107], v[150:153], v[212:215], v[104:107]
	v_mfma_f32_16x16x32_bf16 v[72:75], v[158:161], v[212:215], v[72:75]
	v_mfma_f32_16x16x32_bf16 v[100:103], v[150:153], v[220:223], v[100:103]
	v_mfma_f32_16x16x32_bf16 v[68:71], v[158:161], v[220:223], v[68:71]
	v_mfma_f32_16x16x32_bf16 v[96:99], v[150:153], v[228:231], v[96:99]
	v_mfma_f32_16x16x32_bf16 v[60:63], v[158:161], v[228:231], v[60:63]
	s_setprio 0
	s_setprio 1
	v_mfma_f32_16x16x32_bf16 v[44:47], v[184:187], v[200:203], v[44:47]
	v_mfma_f32_16x16x32_bf16 v[12:15], v[192:195], v[200:203], v[12:15]
	v_mfma_f32_16x16x32_bf16 v[36:39], v[184:187], v[208:211], v[36:39]
	v_mfma_f32_16x16x32_bf16 v[8:11], v[192:195], v[208:211], v[8:11]
	v_mfma_f32_16x16x32_bf16 v[28:31], v[184:187], v[216:219], v[28:31]
	v_mfma_f32_16x16x32_bf16 v[4:7], v[192:195], v[216:219], v[4:7]
	v_mfma_f32_16x16x32_bf16 v[20:23], v[184:187], v[224:227], v[20:23]
	v_mfma_f32_16x16x32_bf16 v[0:3], v[192:195], v[224:227], v[0:3]
	v_mfma_f32_16x16x32_bf16 v[44:47], v[188:191], v[204:207], v[44:47]
	v_mfma_f32_16x16x32_bf16 v[12:15], v[196:199], v[204:207], v[12:15]
	v_mfma_f32_16x16x32_bf16 v[36:39], v[188:191], v[212:215], v[36:39]
	v_mfma_f32_16x16x32_bf16 v[8:11], v[196:199], v[212:215], v[8:11]
	v_mfma_f32_16x16x32_bf16 v[28:31], v[188:191], v[220:223], v[28:31]
	v_mfma_f32_16x16x32_bf16 v[4:7], v[196:199], v[220:223], v[4:7]
	v_mfma_f32_16x16x32_bf16 v[20:23], v[188:191], v[228:231], v[20:23]
	v_mfma_f32_16x16x32_bf16 v[0:3], v[196:199], v[228:231], v[0:3]
	s_barrier
	s_setprio 0
	s_add_i32 s15, 0, 0x18000
	s_add_i32 s17, 0, 0x1c000
	v_add_u32_e32 v158, s15, v164
	v_add_u32_e32 v167, s17, v164
	ds_read_b128 v[146:149], v158
	ds_read_b128 v[150:153], v158 offset:1024
	ds_read_b128 v[154:157], v158 offset:2048
	ds_read_b128 v[158:161], v158 offset:3072
	ds_read_b128 v[184:187], v167
	ds_read_b128 v[188:191], v167 offset:1024
	ds_read_b128 v[192:195], v167 offset:2048
	ds_read_b128 v[196:199], v167 offset:3072
	s_add_u32 s8, s54, 0x50000
	s_addc_u32 s9, s55, 0
	s_mov_b32 m0, s56
	v_lshl_add_u64 v[234:235], s[8:9], 0, v[128:129]
	ds_read_b128 v[200:203], v166 offset:32768
	ds_read_b128 v[204:207], v166 offset:33792
	ds_read_b128 v[208:211], v166 offset:34816
	ds_read_b128 v[212:215], v166 offset:35840
	ds_read_b128 v[216:219], v166 offset:36864
	ds_read_b128 v[220:223], v166 offset:37888
	ds_read_b128 v[224:227], v166 offset:38912
	ds_read_b128 v[228:231], v166 offset:39936
	global_load_lds_dwordx4 v[234:235], off
	v_lshl_add_u64 v[234:235], s[8:9], 0, v[138:139]
	s_mov_b32 m0, s57
	s_nop 0
	global_load_lds_dwordx4 v[234:235], off
	s_waitcnt vmcnt(8)
	s_waitcnt lgkmcnt(0)
	s_setprio 1
	s_barrier
	v_mfma_f32_16x16x32_bf16 v[124:127], v[146:149], v[200:203], v[124:127]
	v_mfma_f32_16x16x32_bf16 v[92:95], v[154:157], v[200:203], v[92:95]
	v_mfma_f32_16x16x32_bf16 v[120:123], v[146:149], v[208:211], v[120:123]
	v_mfma_f32_16x16x32_bf16 v[88:91], v[154:157], v[208:211], v[88:91]
	v_mfma_f32_16x16x32_bf16 v[116:119], v[146:149], v[216:219], v[116:119]
	v_mfma_f32_16x16x32_bf16 v[84:87], v[154:157], v[216:219], v[84:87]
	v_mfma_f32_16x16x32_bf16 v[112:115], v[146:149], v[224:227], v[112:115]
	v_mfma_f32_16x16x32_bf16 v[80:83], v[154:157], v[224:227], v[80:83]
	v_mfma_f32_16x16x32_bf16 v[124:127], v[150:153], v[204:207], v[124:127]
	v_mfma_f32_16x16x32_bf16 v[92:95], v[158:161], v[204:207], v[92:95]
	v_mfma_f32_16x16x32_bf16 v[120:123], v[150:153], v[212:215], v[120:123]
	v_mfma_f32_16x16x32_bf16 v[88:91], v[158:161], v[212:215], v[88:91]
	v_mfma_f32_16x16x32_bf16 v[116:119], v[150:153], v[220:223], v[116:119]
	v_mfma_f32_16x16x32_bf16 v[84:87], v[158:161], v[220:223], v[84:87]
	v_mfma_f32_16x16x32_bf16 v[112:115], v[150:153], v[228:231], v[112:115]
	v_mfma_f32_16x16x32_bf16 v[80:83], v[158:161], v[228:231], v[80:83]
	s_setprio 0
	s_setprio 1
	v_mfma_f32_16x16x32_bf16 v[64:67], v[184:187], v[200:203], v[64:67]
	v_mfma_f32_16x16x32_bf16 v[40:43], v[192:195], v[200:203], v[40:43]
	v_mfma_f32_16x16x32_bf16 v[56:59], v[184:187], v[208:211], v[56:59]
	v_mfma_f32_16x16x32_bf16 v[32:35], v[192:195], v[208:211], v[32:35]
	v_mfma_f32_16x16x32_bf16 v[52:55], v[184:187], v[216:219], v[52:55]
	v_mfma_f32_16x16x32_bf16 v[24:27], v[192:195], v[216:219], v[24:27]
	v_mfma_f32_16x16x32_bf16 v[48:51], v[184:187], v[224:227], v[48:51]
	v_mfma_f32_16x16x32_bf16 v[16:19], v[192:195], v[224:227], v[16:19]
	v_mfma_f32_16x16x32_bf16 v[64:67], v[188:191], v[204:207], v[64:67]
	v_mfma_f32_16x16x32_bf16 v[40:43], v[196:199], v[204:207], v[40:43]
	v_mfma_f32_16x16x32_bf16 v[56:59], v[188:191], v[212:215], v[56:59]
	v_mfma_f32_16x16x32_bf16 v[32:35], v[196:199], v[212:215], v[32:35]
	v_mfma_f32_16x16x32_bf16 v[52:55], v[188:191], v[220:223], v[52:55]
	v_mfma_f32_16x16x32_bf16 v[24:27], v[196:199], v[220:223], v[24:27]
	v_mfma_f32_16x16x32_bf16 v[48:51], v[188:191], v[228:231], v[48:51]
	v_mfma_f32_16x16x32_bf16 v[16:19], v[196:199], v[228:231], v[16:19]
	s_barrier
; #define PG8_STAGE(bufoff, gbase, voff) do { _Pragma("unroll") for (int _i = 0; _i < 2; ++_i) \
;         __builtin_amdgcn_global_load_lds((const unsigned*)((const char*)(gbase) + (voff)[_i]), (LAS unsigned*)(lds + (bufoff) + ldsw + _i * 8192), 16, 0, 0); } while (0)
; #define PG8_LDA(dst, b, h) do { _Pragma("unroll") for (int m = 0; m < 4; ++m) _Pragma("unroll") for (int k = 0; k < 2; ++k) dst[m][k] = *(const LAS bf16x8*)(lds + PG8_SA(b, h) + aoff + m * 2048 + k * 1024); } while (0)
; #define PG8_MMA(ai, bj, At, Bt) do { __builtin_amdgcn_s_setprio(1); _Pragma("unroll") for (int m = 0; m < 4; ++m) _Pragma("unroll") for (int n = 0; n < 2; ++n) _Pragma("unroll") for (int k = 0; k < 2; ++k) \
;         acc[ai][bj][m][n] = __builtin_amdgcn_mfma_f32_16x16x32_bf16(Bt[n][k], At[m][k], acc[ai][bj][m][n], 0, 0, 0); __builtin_amdgcn_s_setprio(0); } while (0)
; #define PG8_WAIT_V(n) asm volatile("s_waitcnt vmcnt(" #n ")" ::: "memory")
; #define PG8_WAIT_L(n) asm volatile("s_waitcnt lgkmcnt(" #n ")" ::: "memory")
; #define PG8_BAR __builtin_amdgcn_s_barrier()
; #define PG8_SCHED __builtin_amdgcn_sched_barrier(0)
; template <class Epi, class Sched>
; __device__ __forceinline__ void gemm_phase(LAS unsigned char* lds, const int K, const Sched& S, const Epi& E) {
;     ...
;             PG8_LDA(At, 1, 1); PG8_STAGE(PG8_SB(1, 0), b3, voffB); PG8_STAGE(PG8_SB(1, 1), b3 + hstep, voffB); PG8_STAGE(PG8_SA(1, 0), a3, voffA);
;             PG8_WAIT_V(8); PG8_WAIT_L(0); PG8_BAR; PG8_MMA(1, 0, At, B0); PG8_MMA(1, 1, At, B1); PG8_BAR; PG8_SCHED;
;         }
;         if (wr == 0) PG8_BAR;
	s_setprio 0
	s_add_i32 s8, s15, s3
	v_lshl_add_u64 v[162:163], v[162:163], 0, s[36:37]
	s_mov_b32 m0, s8
	s_nop 0
	global_load_lds_dwordx4 v[162:163], off
	s_add_i32 m0, s8, 0x2000
	s_add_u32 s8, s52, 0x50080
	v_lshl_add_u64 v[162:163], v[180:181], 0, s[36:37]
	s_addc_u32 s9, s53, 0
	s_add_i32 s15, s17, s3
	global_load_lds_dwordx4 v[162:163], off
	v_lshl_add_u64 v[162:163], s[8:9], 0, v[128:129]
	s_mov_b32 m0, s15
	s_nop 0
	global_load_lds_dwordx4 v[162:163], off
	v_lshl_add_u64 v[162:163], s[8:9], 0, v[138:139]
	s_add_i32 m0, s15, 0x2000
	s_nop 0
	global_load_lds_dwordx4 v[162:163], off
	v_lshl_add_u64 v[162:163], v[182:183], 0, s[36:37]
	s_mov_b32 m0, s58
	s_nop 0
	global_load_lds_dwordx4 v[162:163], off
	v_lshl_add_u64 v[162:163], v[232:233], 0, s[36:37]
	s_mov_b32 m0, s59
	s_nop 0
	global_load_lds_dwordx4 v[162:163], off
	ds_read_b128 v[200:203], v166 offset:49152
	ds_read_b128 v[204:207], v166 offset:50176
	ds_read_b128 v[208:211], v166 offset:51200
	ds_read_b128 v[212:215], v166 offset:52224
	ds_read_b128 v[216:219], v166 offset:53248
	ds_read_b128 v[220:223], v166 offset:54272
	ds_read_b128 v[224:227], v166 offset:55296
	ds_read_b128 v[228:231], v166 offset:56320
	s_waitcnt vmcnt(8)
	s_waitcnt lgkmcnt(0)
	s_setprio 1
	s_barrier
	v_mfma_f32_16x16x32_bf16 v[108:111], v[146:149], v[200:203], v[108:111]
	v_mfma_f32_16x16x32_bf16 v[76:79], v[154:157], v[200:203], v[76:79]
	v_mfma_f32_16x16x32_bf16 v[104:107], v[146:149], v[208:211], v[104:107]
	v_mfma_f32_16x16x32_bf16 v[72:75], v[154:157], v[208:211], v[72:75]
	v_mfma_f32_16x16x32_bf16 v[100:103], v[146:149], v[216:219], v[100:103]
	v_mfma_f32_16x16x32_bf16 v[68:71], v[154:157], v[216:219], v[68:71]
	v_mfma_f32_16x16x32_bf16 v[96:99], v[146:149], v[224:227], v[96:99]
	v_mfma_f32_16x16x32_bf16 v[60:63], v[154:157], v[224:227], v[60:63]
	v_mfma_f32_16x16x32_bf16 v[108:111], v[150:153], v[204:207], v[108:111]
	v_mfma_f32_16x16x32_bf16 v[76:79], v[158:161], v[204:207], v[76:79]
	v_mfma_f32_16x16x32_bf16 v[104:107], v[150:153], v[212:215], v[104:107]
	v_mfma_f32_16x16x32_bf16 v[72:75], v[158:161], v[212:215], v[72:75]
	v_mfma_f32_16x16x32_bf16 v[100:103], v[150:153], v[220:223], v[100:103]
	v_mfma_f32_16x16x32_bf16 v[68:71], v[158:161], v[220:223], v[68:71]
	v_mfma_f32_16x16x32_bf16 v[96:99], v[150:153], v[228:231], v[96:99]
	v_mfma_f32_16x16x32_bf16 v[60:63], v[158:161], v[228:231], v[60:63]
	s_setprio 0
	s_setprio 1
	v_mfma_f32_16x16x32_bf16 v[44:47], v[184:187], v[200:203], v[44:47]
	v_mfma_f32_16x16x32_bf16 v[12:15], v[192:195], v[200:203], v[12:15]
	v_mfma_f32_16x16x32_bf16 v[36:39], v[184:187], v[208:211], v[36:39]
	v_mfma_f32_16x16x32_bf16 v[8:11], v[192:195], v[208:211], v[8:11]
	v_mfma_f32_16x16x32_bf16 v[28:31], v[184:187], v[216:219], v[28:31]
	v_mfma_f32_16x16x32_bf16 v[4:7], v[192:195], v[216:219], v[4:7]
	v_mfma_f32_16x16x32_bf16 v[20:23], v[184:187], v[224:227], v[20:23]
	v_mfma_f32_16x16x32_bf16 v[0:3], v[192:195], v[224:227], v[0:3]
	v_mfma_f32_16x16x32_bf16 v[44:47], v[188:191], v[204:207], v[44:47]
	v_mfma_f32_16x16x32_bf16 v[12:15], v[196:199], v[204:207], v[12:15]
	v_mfma_f32_16x16x32_bf16 v[36:39], v[188:191], v[212:215], v[36:39]
	v_mfma_f32_16x16x32_bf16 v[8:11], v[196:199], v[212:215], v[8:11]
	v_mfma_f32_16x16x32_bf16 v[28:31], v[188:191], v[220:223], v[28:31]
	v_mfma_f32_16x16x32_bf16 v[4:7], v[196:199], v[220:223], v[4:7]
	v_mfma_f32_16x16x32_bf16 v[20:23], v[188:191], v[228:231], v[20:23]
	v_mfma_f32_16x16x32_bf16 v[0:3], v[196:199], v[228:231], v[0:3]
	s_barrier
	s_setprio 0
	s_add_u32 s13, s13, 0x100
	s_addc_u32 s14, s14, 0
	s_cmp_ge_i32 s16, s2
	s_mov_b64 s[8:9], s[50:51]
	s_mov_b32 s15, s16
	s_cbranch_scc0 .LBB0_812
	s_and_b64 vcc, exec, s[40:41]
	s_cbranch_vccz .LBB0_815
	s_barrier

; #define PG8_STAGE(bufoff, gbase, voff) do { _Pragma("unroll") for (int _i = 0; _i < 2; ++_i) \
;         __builtin_amdgcn_global_load_lds((const unsigned*)((const char*)(gbase) + (voff)[_i]), (LAS unsigned*)(lds + (bufoff) + ldsw + _i * 8192), 16, 0, 0); } while (0)
; #define PG8_LDA(dst, b, h) do { _Pragma("unroll") for (int m = 0; m < 4; ++m) _Pragma("unroll") for (int k = 0; k < 2; ++k) dst[m][k] = *(const LAS bf16x8*)(lds + PG8_SA(b, h) + aoff + m * 2048 + k * 1024); } while (0)
; #define PG8_LDB(dst, b, h) do { _Pragma("unroll") for (int n = 0; n < 2; ++n) _Pragma("unroll") for (int k = 0; k < 2; ++k) dst[n][k] = *(const LAS bf16x8*)(lds + PG8_SB(b, h) + boff + n * 2048 + k * 1024); } while (0)
; #define PG8_MMA(ai, bj, At, Bt) do { __builtin_amdgcn_s_setprio(1); _Pragma("unroll") for (int m = 0; m < 4; ++m) _Pragma("unroll") for (int n = 0; n < 2; ++n) _Pragma("unroll") for (int k = 0; k < 2; ++k) \
;         acc[ai][bj][m][n] = __builtin_amdgcn_mfma_f32_16x16x32_bf16(Bt[n][k], At[m][k], acc[ai][bj][m][n], 0, 0, 0); __builtin_amdgcn_s_setprio(0); } while (0)
; #define PG8_WAIT_V(n) asm volatile("s_waitcnt vmcnt(" #n ")" ::: "memory")
; #define PG8_WAIT_L(n) asm volatile("s_waitcnt lgkmcnt(" #n ")" ::: "memory")
; #define PG8_BAR __builtin_amdgcn_s_barrier()
; #define PG8_SCHED __builtin_amdgcn_sched_barrier(0)
; template <class Epi, class Sched>
; __device__ __forceinline__ void gemm_phase(LAS unsigned char* lds, const int K, const Sched& S, const Epi& E) {
;     ...
;             const bool last = (t == nt - 2);
;             const char* a1 = cA + (size_t)(t + 1) * kstep;
;             const char* a2 = last ? nA : cA + (size_t)(t + 2) * kstep; const char* b2 = last ? nB : cB + (size_t)(t + 2) * kstep;
;             const char* a3 = a2 + kstep; const char* b3 = b2 + kstep;
;             PG8_LDB(B0, 0, 0); PG8_LDB(B1, 0, 1); PG8_SCHED; PG8_LDA(At, 0, 0); PG8_STAGE(PG8_SA(1, 1), a1 + hstep, voffA);
;             PG8_WAIT_V(8); PG8_WAIT_L(0); PG8_BAR; PG8_MMA(0, 0, At, B0); PG8_MMA(0, 1, At, B1); PG8_BAR; PG8_SCHED;
;             PG8_LDA(At, 0, 1); PG8_STAGE(PG8_SB(0, 0), b2, voffB); PG8_STAGE(PG8_SB(0, 1), b2 + hstep, voffB); PG8_STAGE(PG8_SA(0, 0), a2, voffA);
;             PG8_WAIT_V(8); PG8_WAIT_L(0); PG8_BAR; PG8_MMA(1, 0, At, B0); PG8_MMA(1, 1, At, B1); PG8_BAR; PG8_SCHED;
.LBB0_963:
	s_add_u32 s5, s56, 0xfffc0080
	s_addc_u32 s9, s57, -1
	s_add_i32 s10, 0, 0x10000
	s_cmp_eq_u32 s4, 12
	s_cselect_b32 s61, s53, s9
	s_cselect_b32 s60, s52, s5
	v_add_u32_e32 v150, s10, v153
	s_cselect_b32 s59, s55, s2
	s_cselect_b32 s58, s54, s1
	s_add_i32 s5, 0, 0x14000
	ds_read_b128 v[156:159], v150
	ds_read_b128 v[160:163], v150 offset:1024
	ds_read_b128 v[164:167], v150 offset:2048
	ds_read_b128 v[180:183], v150 offset:3072
	v_add_u32_e32 v150, s5, v153
	ds_read_b128 v[184:187], v150
	ds_read_b128 v[188:191], v150 offset:1024
	ds_read_b128 v[192:195], v150 offset:2048
	ds_read_b128 v[196:199], v150 offset:3072
	v_lshl_add_u64 v[150:151], s[56:57], 0, v[146:147]
	s_add_i32 m0, s66, 0xc000
	ds_read_b128 v[200:203], v154
	ds_read_b128 v[204:207], v154 offset:1024
	ds_read_b128 v[208:211], v154 offset:2048
	ds_read_b128 v[212:215], v154 offset:3072
	ds_read_b128 v[216:219], v154 offset:4096
	ds_read_b128 v[220:223], v154 offset:5120
	ds_read_b128 v[224:227], v154 offset:6144
	ds_read_b128 v[228:231], v154 offset:7168
	global_load_lds_dwordx4 v[150:151], off
	v_lshl_add_u64 v[150:151], s[56:57], 0, v[148:149]
	s_add_i32 m0, s66, 0xe000
	s_nop 0
	global_load_lds_dwordx4 v[150:151], off
	s_waitcnt vmcnt(8)
	s_waitcnt lgkmcnt(0)
	s_setprio 1
	s_barrier
	v_mfma_f32_16x16x32_bf16 v[124:127], v[156:159], v[200:203], v[124:127]
	v_mfma_f32_16x16x32_bf16 v[116:119], v[164:167], v[200:203], v[116:119]
	v_mfma_f32_16x16x32_bf16 v[108:111], v[156:159], v[208:211], v[108:111]
	v_mfma_f32_16x16x32_bf16 v[100:103], v[164:167], v[208:211], v[100:103]
	v_mfma_f32_16x16x32_bf16 v[92:95], v[156:159], v[216:219], v[92:95]
	v_mfma_f32_16x16x32_bf16 v[84:87], v[164:167], v[216:219], v[84:87]
	v_mfma_f32_16x16x32_bf16 v[76:79], v[156:159], v[224:227], v[76:79]
	v_mfma_f32_16x16x32_bf16 v[68:71], v[164:167], v[224:227], v[68:71]
	v_mfma_f32_16x16x32_bf16 v[124:127], v[160:163], v[204:207], v[124:127]
	v_mfma_f32_16x16x32_bf16 v[116:119], v[180:183], v[204:207], v[116:119]
	v_mfma_f32_16x16x32_bf16 v[108:111], v[160:163], v[212:215], v[108:111]
	v_mfma_f32_16x16x32_bf16 v[100:103], v[180:183], v[212:215], v[100:103]
	v_mfma_f32_16x16x32_bf16 v[92:95], v[160:163], v[220:223], v[92:95]
	v_mfma_f32_16x16x32_bf16 v[84:87], v[180:183], v[220:223], v[84:87]
	v_mfma_f32_16x16x32_bf16 v[76:79], v[160:163], v[228:231], v[76:79]
	v_mfma_f32_16x16x32_bf16 v[68:71], v[180:183], v[228:231], v[68:71]
	s_setprio 0
	s_setprio 1
	v_mfma_f32_16x16x32_bf16 v[120:123], v[184:187], v[200:203], v[120:123]
	v_mfma_f32_16x16x32_bf16 v[112:115], v[192:195], v[200:203], v[112:115]
	v_mfma_f32_16x16x32_bf16 v[104:107], v[184:187], v[208:211], v[104:107]
	v_mfma_f32_16x16x32_bf16 v[96:99], v[192:195], v[208:211], v[96:99]
	v_mfma_f32_16x16x32_bf16 v[88:91], v[184:187], v[216:219], v[88:91]
	v_mfma_f32_16x16x32_bf16 v[80:83], v[192:195], v[216:219], v[80:83]
	v_mfma_f32_16x16x32_bf16 v[72:75], v[184:187], v[224:227], v[72:75]
	v_mfma_f32_16x16x32_bf16 v[64:67], v[192:195], v[224:227], v[64:67]
	v_mfma_f32_16x16x32_bf16 v[120:123], v[188:191], v[204:207], v[120:123]
	v_mfma_f32_16x16x32_bf16 v[112:115], v[196:199], v[204:207], v[112:115]
	v_mfma_f32_16x16x32_bf16 v[104:107], v[188:191], v[212:215], v[104:107]
	v_mfma_f32_16x16x32_bf16 v[96:99], v[196:199], v[212:215], v[96:99]
	v_mfma_f32_16x16x32_bf16 v[88:91], v[188:191], v[220:223], v[88:91]
	v_mfma_f32_16x16x32_bf16 v[80:83], v[196:199], v[220:223], v[80:83]
	v_mfma_f32_16x16x32_bf16 v[72:75], v[188:191], v[228:231], v[72:75]
	v_mfma_f32_16x16x32_bf16 v[64:67], v[196:199], v[228:231], v[64:67]
	s_barrier
	s_setprio 0
	s_add_i32 s9, s10, s63
	v_lshl_add_u64 v[150:151], s[58:59], 0, v[142:143]
	s_mov_b32 m0, s9
	s_nop 0
	global_load_lds_dwordx4 v[150:151], off
	s_add_i32 m0, s9, 0x2000
	s_add_u32 s10, s58, 0x40000
	v_lshl_add_u64 v[232:233], s[58:59], 0, v[138:139]
	s_addc_u32 s11, s59, 0
	s_add_i32 s5, s5, s63
	global_load_lds_dwordx4 v[232:233], off
	v_lshl_add_u64 v[234:235], s[10:11], 0, v[142:143]
	s_mov_b32 m0, s5
	v_lshl_add_u64 v[236:237], s[60:61], 0, v[140:141]
	global_load_lds_dwordx4 v[234:235], off
	v_lshl_add_u64 v[234:235], s[10:11], 0, v[138:139]
	s_add_i32 m0, s5, 0x2000
	s_nop 0
	global_load_lds_dwordx4 v[234:235], off
	v_lshl_add_u64 v[234:235], s[60:61], 0, v[144:145]
	s_mov_b32 m0, s66
	s_nop 0
	global_load_lds_dwordx4 v[234:235], off
	s_mov_b32 m0, s67
	s_nop 0
	global_load_lds_dwordx4 v[236:237], off
	ds_read_b128 v[200:203], v154 offset:16384
	ds_read_b128 v[204:207], v154 offset:17408
	ds_read_b128 v[208:211], v154 offset:18432
	ds_read_b128 v[212:215], v154 offset:19456
	ds_read_b128 v[216:219], v154 offset:20480
	ds_read_b128 v[220:223], v154 offset:21504
	ds_read_b128 v[224:227], v154 offset:22528
	ds_read_b128 v[228:231], v154 offset:23552
	s_waitcnt vmcnt(8)
	s_waitcnt lgkmcnt(0)
	s_setprio 1
	s_barrier
; #define PG8_STAGE(bufoff, gbase, voff) do { _Pragma("unroll") for (int _i = 0; _i < 2; ++_i) \
;         __builtin_amdgcn_global_load_lds((const unsigned*)((const char*)(gbase) + (voff)[_i]), (LAS unsigned*)(lds + (bufoff) + ldsw + _i * 8192), 16, 0, 0); } while (0)
; #define PG8_LDA(dst, b, h) do { _Pragma("unroll") for (int m = 0; m < 4; ++m) _Pragma("unroll") for (int k = 0; k < 2; ++k) dst[m][k] = *(const LAS bf16x8*)(lds + PG8_SA(b, h) + aoff + m * 2048 + k * 1024); } while (0)
; #define PG8_LDB(dst, b, h) do { _Pragma("unroll") for (int n = 0; n < 2; ++n) _Pragma("unroll") for (int k = 0; k < 2; ++k) dst[n][k] = *(const LAS bf16x8*)(lds + PG8_SB(b, h) + boff + n * 2048 + k * 1024); } while (0)
; #define PG8_MMA(ai, bj, At, Bt) do { __builtin_amdgcn_s_setprio(1); _Pragma("unroll") for (int m = 0; m < 4; ++m) _Pragma("unroll") for (int n = 0; n < 2; ++n) _Pragma("unroll") for (int k = 0; k < 2; ++k) \
;         acc[ai][bj][m][n] = __builtin_amdgcn_mfma_f32_16x16x32_bf16(Bt[n][k], At[m][k], acc[ai][bj][m][n], 0, 0, 0); __builtin_amdgcn_s_setprio(0); } while (0)
; #define PG8_WAIT_V(n) asm volatile("s_waitcnt vmcnt(" #n ")" ::: "memory")
; #define PG8_WAIT_L(n) asm volatile("s_waitcnt lgkmcnt(" #n ")" ::: "memory")
; #define PG8_BAR __builtin_amdgcn_s_barrier()
; #define PG8_SCHED __builtin_amdgcn_sched_barrier(0)
; template <class Epi, class Sched>
; __device__ __forceinline__ void gemm_phase(LAS unsigned char* lds, const int K, const Sched& S, const Epi& E) {
;     ...
;             PG8_WAIT_V(8); PG8_WAIT_L(0); PG8_BAR; PG8_MMA(1, 0, At, B0); PG8_MMA(1, 1, At, B1); PG8_BAR; PG8_SCHED;
;             PG8_LDB(B0, 1, 0); PG8_LDB(B1, 1, 1); PG8_SCHED; PG8_LDA(At, 1, 0); PG8_STAGE(PG8_SA(0, 1), a2 + hstep, voffA);
;             PG8_WAIT_V(8); PG8_WAIT_L(0); PG8_BAR; PG8_MMA(0, 0, At, B0); PG8_MMA(0, 1, At, B1); PG8_BAR; PG8_SCHED;
	v_mfma_f32_16x16x32_bf16 v[60:63], v[156:159], v[200:203], v[60:63]
	v_mfma_f32_16x16x32_bf16 v[52:55], v[164:167], v[200:203], v[52:55]
	v_mfma_f32_16x16x32_bf16 v[44:47], v[156:159], v[208:211], v[44:47]
	v_mfma_f32_16x16x32_bf16 v[36:39], v[164:167], v[208:211], v[36:39]
	v_mfma_f32_16x16x32_bf16 v[28:31], v[156:159], v[216:219], v[28:31]
	v_mfma_f32_16x16x32_bf16 v[20:23], v[164:167], v[216:219], v[20:23]
	v_mfma_f32_16x16x32_bf16 v[12:15], v[156:159], v[224:227], v[12:15]
	v_mfma_f32_16x16x32_bf16 v[4:7], v[164:167], v[224:227], v[4:7]
	v_mfma_f32_16x16x32_bf16 v[60:63], v[160:163], v[204:207], v[60:63]
	v_mfma_f32_16x16x32_bf16 v[52:55], v[180:183], v[204:207], v[52:55]
	v_mfma_f32_16x16x32_bf16 v[44:47], v[160:163], v[212:215], v[44:47]
	v_mfma_f32_16x16x32_bf16 v[36:39], v[180:183], v[212:215], v[36:39]
	v_mfma_f32_16x16x32_bf16 v[28:31], v[160:163], v[220:223], v[28:31]
	v_mfma_f32_16x16x32_bf16 v[20:23], v[180:183], v[220:223], v[20:23]
	v_mfma_f32_16x16x32_bf16 v[12:15], v[160:163], v[228:231], v[12:15]
	v_mfma_f32_16x16x32_bf16 v[4:7], v[180:183], v[228:231], v[4:7]
	s_setprio 0
	s_setprio 1
	v_mfma_f32_16x16x32_bf16 v[56:59], v[184:187], v[200:203], v[56:59]
	v_mfma_f32_16x16x32_bf16 v[48:51], v[192:195], v[200:203], v[48:51]
	v_mfma_f32_16x16x32_bf16 v[40:43], v[184:187], v[208:211], v[40:43]
	v_mfma_f32_16x16x32_bf16 v[32:35], v[192:195], v[208:211], v[32:35]
	v_mfma_f32_16x16x32_bf16 v[24:27], v[184:187], v[216:219], v[24:27]
	v_mfma_f32_16x16x32_bf16 v[16:19], v[192:195], v[216:219], v[16:19]
	v_mfma_f32_16x16x32_bf16 v[8:11], v[184:187], v[224:227], v[8:11]
	v_mfma_f32_16x16x32_bf16 v[0:3], v[192:195], v[224:227], v[0:3]
	v_mfma_f32_16x16x32_bf16 v[56:59], v[188:191], v[204:207], v[56:59]
	v_mfma_f32_16x16x32_bf16 v[48:51], v[196:199], v[204:207], v[48:51]
	v_mfma_f32_16x16x32_bf16 v[40:43], v[188:191], v[212:215], v[40:43]
	v_mfma_f32_16x16x32_bf16 v[32:35], v[196:199], v[212:215], v[32:35]
	v_mfma_f32_16x16x32_bf16 v[24:27], v[188:191], v[220:223], v[24:27]
	v_mfma_f32_16x16x32_bf16 v[16:19], v[196:199], v[220:223], v[16:19]
	v_mfma_f32_16x16x32_bf16 v[8:11], v[188:191], v[228:231], v[8:11]
	v_mfma_f32_16x16x32_bf16 v[0:3], v[196:199], v[228:231], v[0:3]
	s_barrier
	s_setprio 0
	s_add_i32 s5, 0, 0x18000
	v_add_u32_e32 v155, s5, v153
	s_add_i32 s9, 0, 0x1c000
	ds_read_b128 v[156:159], v155
	ds_read_b128 v[160:163], v155 offset:1024
	ds_read_b128 v[164:167], v155 offset:2048
	ds_read_b128 v[180:183], v155 offset:3072
	v_add_u32_e32 v155, s9, v153
	ds_read_b128 v[184:187], v155
	ds_read_b128 v[188:191], v155 offset:1024
	ds_read_b128 v[192:195], v155 offset:2048
	ds_read_b128 v[196:199], v155 offset:3072
	s_add_u32 s10, s60, 0x40000
	s_addc_u32 s11, s61, 0
	s_mov_b32 m0, s68
	v_lshl_add_u64 v[238:239], s[10:11], 0, v[144:145]
	ds_read_b128 v[200:203], v154 offset:32768
	ds_read_b128 v[204:207], v154 offset:33792
	ds_read_b128 v[208:211], v154 offset:34816
	ds_read_b128 v[212:215], v154 offset:35840
	ds_read_b128 v[216:219], v154 offset:36864
	ds_read_b128 v[220:223], v154 offset:37888
	ds_read_b128 v[224:227], v154 offset:38912
	ds_read_b128 v[228:231], v154 offset:39936
	global_load_lds_dwordx4 v[238:239], off
	v_lshl_add_u64 v[238:239], s[10:11], 0, v[140:141]
	s_mov_b32 m0, s69
	s_nop 0
	global_load_lds_dwordx4 v[238:239], off
	s_waitcnt vmcnt(8)
	s_waitcnt lgkmcnt(0)
	s_setprio 1
	s_barrier
	v_mfma_f32_16x16x32_bf16 v[124:127], v[156:159], v[200:203], v[124:127]
	v_mfma_f32_16x16x32_bf16 v[116:119], v[164:167], v[200:203], v[116:119]
	v_mfma_f32_16x16x32_bf16 v[108:111], v[156:159], v[208:211], v[108:111]
	v_mfma_f32_16x16x32_bf16 v[100:103], v[164:167], v[208:211], v[100:103]
	v_mfma_f32_16x16x32_bf16 v[92:95], v[156:159], v[216:219], v[92:95]
	v_mfma_f32_16x16x32_bf16 v[84:87], v[164:167], v[216:219], v[84:87]
	v_mfma_f32_16x16x32_bf16 v[76:79], v[156:159], v[224:227], v[76:79]
	v_mfma_f32_16x16x32_bf16 v[68:71], v[164:167], v[224:227], v[68:71]
	v_mfma_f32_16x16x32_bf16 v[124:127], v[160:163], v[204:207], v[124:127]
	v_mfma_f32_16x16x32_bf16 v[116:119], v[180:183], v[204:207], v[116:119]
	v_mfma_f32_16x16x32_bf16 v[108:111], v[160:163], v[212:215], v[108:111]
	v_mfma_f32_16x16x32_bf16 v[100:103], v[180:183], v[212:215], v[100:103]
	v_mfma_f32_16x16x32_bf16 v[92:95], v[160:163], v[220:223], v[92:95]
	v_mfma_f32_16x16x32_bf16 v[84:87], v[180:183], v[220:223], v[84:87]
	v_mfma_f32_16x16x32_bf16 v[76:79], v[160:163], v[228:231], v[76:79]
	v_mfma_f32_16x16x32_bf16 v[68:71], v[180:183], v[228:231], v[68:71]
	s_setprio 0
	s_setprio 1
	v_mfma_f32_16x16x32_bf16 v[120:123], v[184:187], v[200:203], v[120:123]
	v_mfma_f32_16x16x32_bf16 v[112:115], v[192:195], v[200:203], v[112:115]
	v_mfma_f32_16x16x32_bf16 v[104:107], v[184:187], v[208:211], v[104:107]
	v_mfma_f32_16x16x32_bf16 v[96:99], v[192:195], v[208:211], v[96:99]
	v_mfma_f32_16x16x32_bf16 v[88:91], v[184:187], v[216:219], v[88:91]
	v_mfma_f32_16x16x32_bf16 v[80:83], v[192:195], v[216:219], v[80:83]
	v_mfma_f32_16x16x32_bf16 v[72:75], v[184:187], v[224:227], v[72:75]
	v_mfma_f32_16x16x32_bf16 v[64:67], v[192:195], v[224:227], v[64:67]
	v_mfma_f32_16x16x32_bf16 v[120:123], v[188:191], v[204:207], v[120:123]
	v_mfma_f32_16x16x32_bf16 v[112:115], v[196:199], v[204:207], v[112:115]
	v_mfma_f32_16x16x32_bf16 v[104:107], v[188:191], v[212:215], v[104:107]
	v_mfma_f32_16x16x32_bf16 v[96:99], v[196:199], v[212:215], v[96:99]
	v_mfma_f32_16x16x32_bf16 v[88:91], v[188:191], v[220:223], v[88:91]
	v_mfma_f32_16x16x32_bf16 v[80:83], v[196:199], v[220:223], v[80:83]
	v_mfma_f32_16x16x32_bf16 v[72:75], v[188:191], v[228:231], v[72:75]
	v_mfma_f32_16x16x32_bf16 v[64:67], v[196:199], v[228:231], v[64:67]
	s_barrier
; #define PG8_STAGE(bufoff, gbase, voff) do { _Pragma("unroll") for (int _i = 0; _i < 2; ++_i) \
;         __builtin_amdgcn_global_load_lds((const unsigned*)((const char*)(gbase) + (voff)[_i]), (LAS unsigned*)(lds + (bufoff) + ldsw + _i * 8192), 16, 0, 0); } while (0)
; #define PG8_LDA(dst, b, h) do { _Pragma("unroll") for (int m = 0; m < 4; ++m) _Pragma("unroll") for (int k = 0; k < 2; ++k) dst[m][k] = *(const LAS bf16x8*)(lds + PG8_SA(b, h) + aoff + m * 2048 + k * 1024); } while (0)
; #define PG8_MMA(ai, bj, At, Bt) do { __builtin_amdgcn_s_setprio(1); _Pragma("unroll") for (int m = 0; m < 4; ++m) _Pragma("unroll") for (int n = 0; n < 2; ++n) _Pragma("unroll") for (int k = 0; k < 2; ++k) \
;         acc[ai][bj][m][n] = __builtin_amdgcn_mfma_f32_16x16x32_bf16(Bt[n][k], At[m][k], acc[ai][bj][m][n], 0, 0, 0); __builtin_amdgcn_s_setprio(0); } while (0)
; #define PG8_WAIT_V(n) asm volatile("s_waitcnt vmcnt(" #n ")" ::: "memory")
; #define PG8_WAIT_L(n) asm volatile("s_waitcnt lgkmcnt(" #n ")" ::: "memory")
; #define PG8_BAR __builtin_amdgcn_s_barrier()
; #define PG8_SCHED __builtin_amdgcn_sched_barrier(0)
; template <class Epi, class Sched>
; __device__ __forceinline__ void gemm_phase(LAS unsigned char* lds, const int K, const Sched& S, const Epi& E) {
;     ...
;             PG8_LDA(At, 1, 1); PG8_STAGE(PG8_SB(1, 0), b3, voffB); PG8_STAGE(PG8_SB(1, 1), b3 + hstep, voffB); PG8_STAGE(PG8_SA(1, 0), a3, voffA);
;             PG8_WAIT_V(8); PG8_WAIT_L(0); PG8_BAR; PG8_MMA(1, 0, At, B0); PG8_MMA(1, 1, At, B1); PG8_BAR; PG8_SCHED;
;         }
;         if (wr == 0) PG8_BAR;
	s_setprio 0
	s_add_i32 s5, s5, s63
	v_lshl_add_u64 v[150:151], v[150:151], 0, s[36:37]
	s_mov_b32 m0, s5
	s_nop 0
	global_load_lds_dwordx4 v[150:151], off
	s_add_i32 m0, s5, 0x2000
	s_add_u32 s10, s58, 0x40080
	v_lshl_add_u64 v[150:151], v[232:233], 0, s[36:37]
	s_addc_u32 s11, s59, 0
	s_add_i32 s5, s9, s63
	global_load_lds_dwordx4 v[150:151], off
	v_lshl_add_u64 v[150:151], s[10:11], 0, v[142:143]
	s_mov_b32 m0, s5
	s_nop 0
	global_load_lds_dwordx4 v[150:151], off
	v_lshl_add_u64 v[150:151], s[10:11], 0, v[138:139]
	s_add_i32 m0, s5, 0x2000
	s_nop 0
	global_load_lds_dwordx4 v[150:151], off
	v_lshl_add_u64 v[150:151], v[234:235], 0, s[36:37]
	s_mov_b32 m0, s70
	s_nop 0
	global_load_lds_dwordx4 v[150:151], off
	v_lshl_add_u64 v[150:151], v[236:237], 0, s[36:37]
	s_mov_b32 m0, s71
	s_nop 0
	global_load_lds_dwordx4 v[150:151], off
	ds_read_b128 v[200:203], v154 offset:49152
	ds_read_b128 v[204:207], v154 offset:50176
	ds_read_b128 v[208:211], v154 offset:51200
	ds_read_b128 v[212:215], v154 offset:52224
	ds_read_b128 v[216:219], v154 offset:53248
	ds_read_b128 v[220:223], v154 offset:54272
	ds_read_b128 v[224:227], v154 offset:55296
	ds_read_b128 v[228:231], v154 offset:56320
	s_waitcnt vmcnt(8)
	s_waitcnt lgkmcnt(0)
	s_setprio 1
	s_barrier
	v_mfma_f32_16x16x32_bf16 v[60:63], v[156:159], v[200:203], v[60:63]
	v_mfma_f32_16x16x32_bf16 v[52:55], v[164:167], v[200:203], v[52:55]
	v_mfma_f32_16x16x32_bf16 v[44:47], v[156:159], v[208:211], v[44:47]
	v_mfma_f32_16x16x32_bf16 v[36:39], v[164:167], v[208:211], v[36:39]
	v_mfma_f32_16x16x32_bf16 v[28:31], v[156:159], v[216:219], v[28:31]
	v_mfma_f32_16x16x32_bf16 v[20:23], v[164:167], v[216:219], v[20:23]
	v_mfma_f32_16x16x32_bf16 v[12:15], v[156:159], v[224:227], v[12:15]
	v_mfma_f32_16x16x32_bf16 v[4:7], v[164:167], v[224:227], v[4:7]
	v_mfma_f32_16x16x32_bf16 v[60:63], v[160:163], v[204:207], v[60:63]
	v_mfma_f32_16x16x32_bf16 v[52:55], v[180:183], v[204:207], v[52:55]
	v_mfma_f32_16x16x32_bf16 v[44:47], v[160:163], v[212:215], v[44:47]
	v_mfma_f32_16x16x32_bf16 v[36:39], v[180:183], v[212:215], v[36:39]
	v_mfma_f32_16x16x32_bf16 v[28:31], v[160:163], v[220:223], v[28:31]
	v_mfma_f32_16x16x32_bf16 v[20:23], v[180:183], v[220:223], v[20:23]
	v_mfma_f32_16x16x32_bf16 v[12:15], v[160:163], v[228:231], v[12:15]
	v_mfma_f32_16x16x32_bf16 v[4:7], v[180:183], v[228:231], v[4:7]
	s_setprio 0
	s_setprio 1
	v_mfma_f32_16x16x32_bf16 v[56:59], v[184:187], v[200:203], v[56:59]
	v_mfma_f32_16x16x32_bf16 v[48:51], v[192:195], v[200:203], v[48:51]
	v_mfma_f32_16x16x32_bf16 v[40:43], v[184:187], v[208:211], v[40:43]
	v_mfma_f32_16x16x32_bf16 v[32:35], v[192:195], v[208:211], v[32:35]
	v_mfma_f32_16x16x32_bf16 v[24:27], v[184:187], v[216:219], v[24:27]
	v_mfma_f32_16x16x32_bf16 v[16:19], v[192:195], v[216:219], v[16:19]
	v_mfma_f32_16x16x32_bf16 v[8:11], v[184:187], v[224:227], v[8:11]
	v_mfma_f32_16x16x32_bf16 v[0:3], v[192:195], v[224:227], v[0:3]
	v_mfma_f32_16x16x32_bf16 v[56:59], v[188:191], v[204:207], v[56:59]
	v_mfma_f32_16x16x32_bf16 v[48:51], v[196:199], v[204:207], v[48:51]
	v_mfma_f32_16x16x32_bf16 v[40:43], v[188:191], v[212:215], v[40:43]
	v_mfma_f32_16x16x32_bf16 v[32:35], v[196:199], v[212:215], v[32:35]
	v_mfma_f32_16x16x32_bf16 v[24:27], v[188:191], v[220:223], v[24:27]
	v_mfma_f32_16x16x32_bf16 v[16:19], v[196:199], v[220:223], v[16:19]
	v_mfma_f32_16x16x32_bf16 v[8:11], v[188:191], v[228:231], v[8:11]
	v_mfma_f32_16x16x32_bf16 v[0:3], v[196:199], v[228:231], v[0:3]
	s_barrier
	s_setprio 0
	s_add_i32 s4, s4, 2
	s_add_u32 s56, s56, 0x100
	s_addc_u32 s57, s57, 0
	s_add_u32 s1, s1, 0x100
	s_addc_u32 s2, s2, 0
	s_cmp_gt_u32 s4, 13
	s_cbranch_scc0 .LBB0_963
	s_and_b64 vcc, exec, s[46:47]
	s_cbranch_vccz .LBB0_966
	s_barrier

; #define PG8_STAGE(bufoff, gbase, voff) do { _Pragma("unroll") for (int _i = 0; _i < 2; ++_i) \
;         __builtin_amdgcn_global_load_lds((const unsigned*)((const char*)(gbase) + (voff)[_i]), (LAS unsigned*)(lds + (bufoff) + ldsw + _i * 8192), 16, 0, 0); } while (0)
; #define PG8_LDA(dst, b, h) do { _Pragma("unroll") for (int m = 0; m < 4; ++m) _Pragma("unroll") for (int k = 0; k < 2; ++k) dst[m][k] = *(const LAS bf16x8*)(lds + PG8_SA(b, h) + aoff + m * 2048 + k * 1024); } while (0)
; #define PG8_LDB(dst, b, h) do { _Pragma("unroll") for (int n = 0; n < 2; ++n) _Pragma("unroll") for (int k = 0; k < 2; ++k) dst[n][k] = *(const LAS bf16x8*)(lds + PG8_SB(b, h) + boff + n * 2048 + k * 1024); } while (0)
; #define PG8_MMA(ai, bj, At, Bt) do { __builtin_amdgcn_s_setprio(1); _Pragma("unroll") for (int m = 0; m < 4; ++m) _Pragma("unroll") for (int n = 0; n < 2; ++n) _Pragma("unroll") for (int k = 0; k < 2; ++k) \
;         acc[ai][bj][m][n] = __builtin_amdgcn_mfma_f32_16x16x32_bf16(Bt[n][k], At[m][k], acc[ai][bj][m][n], 0, 0, 0); __builtin_amdgcn_s_setprio(0); } while (0)
; #define PG8_WAIT_V(n) asm volatile("s_waitcnt vmcnt(" #n ")" ::: "memory")
; #define PG8_WAIT_L(n) asm volatile("s_waitcnt lgkmcnt(" #n ")" ::: "memory")
; #define PG8_BAR __builtin_amdgcn_s_barrier()
; #define PG8_SCHED __builtin_amdgcn_sched_barrier(0)
; template <class Epi, class Sched>
; __device__ __forceinline__ void gemm_phase(LAS unsigned char* lds, const int K, const Sched& S, const Epi& E) {
;     ...
;             const bool last = (t == nt - 2);
;             const char* a1 = cA + (size_t)(t + 1) * kstep;
;             const char* a2 = last ? nA : cA + (size_t)(t + 2) * kstep; const char* b2 = last ? nB : cB + (size_t)(t + 2) * kstep;
;             const char* a3 = a2 + kstep; const char* b3 = b2 + kstep;
;             PG8_LDB(B0, 0, 0); PG8_LDB(B1, 0, 1); PG8_SCHED; PG8_LDA(At, 0, 0); PG8_STAGE(PG8_SA(1, 1), a1 + hstep, voffA);
;             PG8_WAIT_V(8); PG8_WAIT_L(0); PG8_BAR; PG8_MMA(0, 0, At, B0); PG8_MMA(0, 1, At, B1); PG8_BAR; PG8_SCHED;
;             PG8_LDA(At, 0, 1); PG8_STAGE(PG8_SB(0, 0), b2, voffB); PG8_STAGE(PG8_SB(0, 1), b2 + hstep, voffB); PG8_STAGE(PG8_SA(0, 0), a2, voffA);
;             PG8_WAIT_V(8); PG8_WAIT_L(0); PG8_BAR; PG8_MMA(1, 0, At, B0); PG8_MMA(1, 1, At, B1); PG8_BAR; PG8_SCHED;
.LBB0_1073:
	s_add_i32 s13, s12, 2
	s_add_u32 s52, s8, 0x100
	s_addc_u32 s53, s9, 0
	s_add_i32 s14, 0, 0x10000
	s_cmp_eq_u32 s5, s12
	s_cselect_b32 s57, s0, s53
	s_cselect_b32 s56, s1, s52
	s_cselect_b32 s55, s2, s11
	s_cselect_b32 s54, s4, s10
	s_add_i32 s12, 0, 0x14000
	v_add_u32_e32 v158, s14, v164
	v_add_u32_e32 v162, s12, v164
	ds_read_b128 v[146:149], v158
	ds_read_b128 v[150:153], v158 offset:1024
	ds_read_b128 v[154:157], v158 offset:2048
	ds_read_b128 v[158:161], v158 offset:3072
	ds_read_b128 v[180:183], v162
	ds_read_b128 v[184:187], v162 offset:1024
	ds_read_b128 v[188:191], v162 offset:2048
	ds_read_b128 v[192:195], v162 offset:3072
	v_lshl_add_u64 v[162:163], s[8:9], 0, v[142:143]
	s_add_i32 m0, s61, 0xc000
	ds_read_b128 v[196:199], v166
	ds_read_b128 v[200:203], v166 offset:1024
	ds_read_b128 v[204:207], v166 offset:2048
	ds_read_b128 v[208:211], v166 offset:3072
	ds_read_b128 v[212:215], v166 offset:4096
	ds_read_b128 v[216:219], v166 offset:5120
	ds_read_b128 v[220:223], v166 offset:6144
	ds_read_b128 v[224:227], v166 offset:7168
	global_load_lds_dwordx4 v[162:163], off
	v_lshl_add_u64 v[162:163], s[8:9], 0, v[144:145]
	s_add_i32 m0, s61, 0xe000
	s_nop 0
	global_load_lds_dwordx4 v[162:163], off
	s_waitcnt vmcnt(8)
	s_waitcnt lgkmcnt(0)
	s_setprio 1
	s_barrier
	v_mfma_f32_16x16x32_bf16 v[124:127], v[146:149], v[196:199], v[124:127]
	v_mfma_f32_16x16x32_bf16 v[92:95], v[154:157], v[196:199], v[92:95]
	v_mfma_f32_16x16x32_bf16 v[120:123], v[146:149], v[204:207], v[120:123]
	v_mfma_f32_16x16x32_bf16 v[88:91], v[154:157], v[204:207], v[88:91]
	v_mfma_f32_16x16x32_bf16 v[116:119], v[146:149], v[212:215], v[116:119]
	v_mfma_f32_16x16x32_bf16 v[84:87], v[154:157], v[212:215], v[84:87]
	v_mfma_f32_16x16x32_bf16 v[112:115], v[146:149], v[220:223], v[112:115]
	v_mfma_f32_16x16x32_bf16 v[80:83], v[154:157], v[220:223], v[80:83]
	v_mfma_f32_16x16x32_bf16 v[124:127], v[150:153], v[200:203], v[124:127]
	v_mfma_f32_16x16x32_bf16 v[92:95], v[158:161], v[200:203], v[92:95]
	v_mfma_f32_16x16x32_bf16 v[120:123], v[150:153], v[208:211], v[120:123]
	v_mfma_f32_16x16x32_bf16 v[88:91], v[158:161], v[208:211], v[88:91]
	v_mfma_f32_16x16x32_bf16 v[116:119], v[150:153], v[216:219], v[116:119]
	v_mfma_f32_16x16x32_bf16 v[84:87], v[158:161], v[216:219], v[84:87]
	v_mfma_f32_16x16x32_bf16 v[112:115], v[150:153], v[224:227], v[112:115]
	v_mfma_f32_16x16x32_bf16 v[80:83], v[158:161], v[224:227], v[80:83]
	s_setprio 0
	s_setprio 1
	v_mfma_f32_16x16x32_bf16 v[60:63], v[180:183], v[196:199], v[60:63]
	v_mfma_f32_16x16x32_bf16 v[28:31], v[188:191], v[196:199], v[28:31]
	v_mfma_f32_16x16x32_bf16 v[56:59], v[180:183], v[204:207], v[56:59]
	v_mfma_f32_16x16x32_bf16 v[24:27], v[188:191], v[204:207], v[24:27]
	v_mfma_f32_16x16x32_bf16 v[52:55], v[180:183], v[212:215], v[52:55]
	v_mfma_f32_16x16x32_bf16 v[20:23], v[188:191], v[212:215], v[20:23]
	v_mfma_f32_16x16x32_bf16 v[48:51], v[180:183], v[220:223], v[48:51]
	v_mfma_f32_16x16x32_bf16 v[16:19], v[188:191], v[220:223], v[16:19]
	v_mfma_f32_16x16x32_bf16 v[60:63], v[184:187], v[200:203], v[60:63]
	v_mfma_f32_16x16x32_bf16 v[28:31], v[192:195], v[200:203], v[28:31]
	v_mfma_f32_16x16x32_bf16 v[56:59], v[184:187], v[208:211], v[56:59]
	v_mfma_f32_16x16x32_bf16 v[24:27], v[192:195], v[208:211], v[24:27]
	v_mfma_f32_16x16x32_bf16 v[52:55], v[184:187], v[216:219], v[52:55]
	v_mfma_f32_16x16x32_bf16 v[20:23], v[192:195], v[216:219], v[20:23]
	v_mfma_f32_16x16x32_bf16 v[48:51], v[184:187], v[224:227], v[48:51]
	v_mfma_f32_16x16x32_bf16 v[16:19], v[192:195], v[224:227], v[16:19]
	s_barrier
	s_setprio 0
	s_add_i32 s8, s14, s60
	v_lshl_add_u64 v[162:163], s[54:55], 0, v[128:129]
	s_mov_b32 m0, s8
	s_nop 0
	global_load_lds_dwordx4 v[162:163], off
	s_add_i32 m0, s8, 0x2000
	s_add_u32 s8, s54, 0xb0000
	v_lshl_add_u64 v[228:229], s[54:55], 0, v[138:139]
	s_addc_u32 s9, s55, 0
	s_add_i32 s12, s12, s60
	global_load_lds_dwordx4 v[228:229], off
	v_lshl_add_u64 v[230:231], s[8:9], 0, v[128:129]
	s_mov_b32 m0, s12
	v_lshl_add_u64 v[232:233], s[56:57], 0, v[138:139]
	global_load_lds_dwordx4 v[230:231], off
	v_lshl_add_u64 v[230:231], s[8:9], 0, v[138:139]
	s_add_i32 m0, s12, 0x2000
	s_nop 0
	global_load_lds_dwordx4 v[230:231], off
	v_lshl_add_u64 v[230:231], s[56:57], 0, v[128:129]
	s_mov_b32 m0, s61
	s_nop 0
	global_load_lds_dwordx4 v[230:231], off
	s_mov_b32 m0, s63
	s_nop 0
	global_load_lds_dwordx4 v[232:233], off
	ds_read_b128 v[196:199], v166 offset:16384
	ds_read_b128 v[200:203], v166 offset:17408
	ds_read_b128 v[204:207], v166 offset:18432
	ds_read_b128 v[208:211], v166 offset:19456
	ds_read_b128 v[212:215], v166 offset:20480
	ds_read_b128 v[216:219], v166 offset:21504
	ds_read_b128 v[220:223], v166 offset:22528
	ds_read_b128 v[224:227], v166 offset:23552
	s_waitcnt vmcnt(8)
	s_waitcnt lgkmcnt(0)
	s_setprio 1
	s_barrier
; #define PG8_STAGE(bufoff, gbase, voff) do { _Pragma("unroll") for (int _i = 0; _i < 2; ++_i) \
;         __builtin_amdgcn_global_load_lds((const unsigned*)((const char*)(gbase) + (voff)[_i]), (LAS unsigned*)(lds + (bufoff) + ldsw + _i * 8192), 16, 0, 0); } while (0)
; #define PG8_LDA(dst, b, h) do { _Pragma("unroll") for (int m = 0; m < 4; ++m) _Pragma("unroll") for (int k = 0; k < 2; ++k) dst[m][k] = *(const LAS bf16x8*)(lds + PG8_SA(b, h) + aoff + m * 2048 + k * 1024); } while (0)
; #define PG8_LDB(dst, b, h) do { _Pragma("unroll") for (int n = 0; n < 2; ++n) _Pragma("unroll") for (int k = 0; k < 2; ++k) dst[n][k] = *(const LAS bf16x8*)(lds + PG8_SB(b, h) + boff + n * 2048 + k * 1024); } while (0)
; #define PG8_MMA(ai, bj, At, Bt) do { __builtin_amdgcn_s_setprio(1); _Pragma("unroll") for (int m = 0; m < 4; ++m) _Pragma("unroll") for (int n = 0; n < 2; ++n) _Pragma("unroll") for (int k = 0; k < 2; ++k) \
;         acc[ai][bj][m][n] = __builtin_amdgcn_mfma_f32_16x16x32_bf16(Bt[n][k], At[m][k], acc[ai][bj][m][n], 0, 0, 0); __builtin_amdgcn_s_setprio(0); } while (0)
; #define PG8_WAIT_V(n) asm volatile("s_waitcnt vmcnt(" #n ")" ::: "memory")
; #define PG8_WAIT_L(n) asm volatile("s_waitcnt lgkmcnt(" #n ")" ::: "memory")
; #define PG8_BAR __builtin_amdgcn_s_barrier()
; #define PG8_SCHED __builtin_amdgcn_sched_barrier(0)
; template <class Epi, class Sched>
; __device__ __forceinline__ void gemm_phase(LAS unsigned char* lds, const int K, const Sched& S, const Epi& E) {
;     ...
;             PG8_WAIT_V(8); PG8_WAIT_L(0); PG8_BAR; PG8_MMA(1, 0, At, B0); PG8_MMA(1, 1, At, B1); PG8_BAR; PG8_SCHED;
;             PG8_LDB(B0, 1, 0); PG8_LDB(B1, 1, 1); PG8_SCHED; PG8_LDA(At, 1, 0); PG8_STAGE(PG8_SA(0, 1), a2 + hstep, voffA);
;             PG8_WAIT_V(8); PG8_WAIT_L(0); PG8_BAR; PG8_MMA(0, 0, At, B0); PG8_MMA(0, 1, At, B1); PG8_BAR; PG8_SCHED;
	v_mfma_f32_16x16x32_bf16 v[108:111], v[146:149], v[196:199], v[108:111]
	v_mfma_f32_16x16x32_bf16 v[76:79], v[154:157], v[196:199], v[76:79]
	v_mfma_f32_16x16x32_bf16 v[104:107], v[146:149], v[204:207], v[104:107]
	v_mfma_f32_16x16x32_bf16 v[72:75], v[154:157], v[204:207], v[72:75]
	v_mfma_f32_16x16x32_bf16 v[100:103], v[146:149], v[212:215], v[100:103]
	v_mfma_f32_16x16x32_bf16 v[68:71], v[154:157], v[212:215], v[68:71]
	v_mfma_f32_16x16x32_bf16 v[96:99], v[146:149], v[220:223], v[96:99]
	v_mfma_f32_16x16x32_bf16 v[64:67], v[154:157], v[220:223], v[64:67]
	v_mfma_f32_16x16x32_bf16 v[108:111], v[150:153], v[200:203], v[108:111]
	v_mfma_f32_16x16x32_bf16 v[76:79], v[158:161], v[200:203], v[76:79]
	v_mfma_f32_16x16x32_bf16 v[104:107], v[150:153], v[208:211], v[104:107]
	v_mfma_f32_16x16x32_bf16 v[72:75], v[158:161], v[208:211], v[72:75]
	v_mfma_f32_16x16x32_bf16 v[100:103], v[150:153], v[216:219], v[100:103]
	v_mfma_f32_16x16x32_bf16 v[68:71], v[158:161], v[216:219], v[68:71]
	v_mfma_f32_16x16x32_bf16 v[96:99], v[150:153], v[224:227], v[96:99]
	v_mfma_f32_16x16x32_bf16 v[64:67], v[158:161], v[224:227], v[64:67]
	s_setprio 0
	s_setprio 1
	v_mfma_f32_16x16x32_bf16 v[44:47], v[180:183], v[196:199], v[44:47]
	v_mfma_f32_16x16x32_bf16 v[12:15], v[188:191], v[196:199], v[12:15]
	v_mfma_f32_16x16x32_bf16 v[40:43], v[180:183], v[204:207], v[40:43]
	v_mfma_f32_16x16x32_bf16 v[8:11], v[188:191], v[204:207], v[8:11]
	v_mfma_f32_16x16x32_bf16 v[36:39], v[180:183], v[212:215], v[36:39]
	v_mfma_f32_16x16x32_bf16 v[4:7], v[188:191], v[212:215], v[4:7]
	v_mfma_f32_16x16x32_bf16 v[32:35], v[180:183], v[220:223], v[32:35]
	v_mfma_f32_16x16x32_bf16 v[0:3], v[188:191], v[220:223], v[0:3]
	v_mfma_f32_16x16x32_bf16 v[44:47], v[184:187], v[200:203], v[44:47]
	v_mfma_f32_16x16x32_bf16 v[12:15], v[192:195], v[200:203], v[12:15]
	v_mfma_f32_16x16x32_bf16 v[40:43], v[184:187], v[208:211], v[40:43]
	v_mfma_f32_16x16x32_bf16 v[8:11], v[192:195], v[208:211], v[8:11]
	v_mfma_f32_16x16x32_bf16 v[36:39], v[184:187], v[216:219], v[36:39]
	v_mfma_f32_16x16x32_bf16 v[4:7], v[192:195], v[216:219], v[4:7]
	v_mfma_f32_16x16x32_bf16 v[32:35], v[184:187], v[224:227], v[32:35]
	v_mfma_f32_16x16x32_bf16 v[0:3], v[192:195], v[224:227], v[0:3]
	s_barrier
	s_setprio 0
	s_add_i32 s12, 0, 0x18000
	s_add_i32 s14, 0, 0x1c000
	v_add_u32_e32 v158, s12, v164
	v_add_u32_e32 v167, s14, v164
	ds_read_b128 v[146:149], v158
	ds_read_b128 v[150:153], v158 offset:1024
	ds_read_b128 v[154:157], v158 offset:2048
	ds_read_b128 v[158:161], v158 offset:3072
	ds_read_b128 v[180:183], v167
	ds_read_b128 v[184:187], v167 offset:1024
	ds_read_b128 v[188:191], v167 offset:2048
	ds_read_b128 v[192:195], v167 offset:3072
	s_add_u32 s8, s56, 0xb0000
	s_addc_u32 s9, s57, 0
	s_mov_b32 m0, s64
	v_lshl_add_u64 v[234:235], s[8:9], 0, v[128:129]
	ds_read_b128 v[196:199], v166 offset:32768
	ds_read_b128 v[200:203], v166 offset:33792
	ds_read_b128 v[204:207], v166 offset:34816
	ds_read_b128 v[208:211], v166 offset:35840
	ds_read_b128 v[212:215], v166 offset:36864
	ds_read_b128 v[216:219], v166 offset:37888
	ds_read_b128 v[220:223], v166 offset:38912
	ds_read_b128 v[224:227], v166 offset:39936
	global_load_lds_dwordx4 v[234:235], off
	v_lshl_add_u64 v[234:235], s[8:9], 0, v[138:139]
	s_mov_b32 m0, s65
	s_nop 0
	global_load_lds_dwordx4 v[234:235], off
	s_waitcnt vmcnt(8)
	s_waitcnt lgkmcnt(0)
	s_setprio 1
	s_barrier
	v_mfma_f32_16x16x32_bf16 v[124:127], v[146:149], v[196:199], v[124:127]
	v_mfma_f32_16x16x32_bf16 v[92:95], v[154:157], v[196:199], v[92:95]
	v_mfma_f32_16x16x32_bf16 v[120:123], v[146:149], v[204:207], v[120:123]
	v_mfma_f32_16x16x32_bf16 v[88:91], v[154:157], v[204:207], v[88:91]
	v_mfma_f32_16x16x32_bf16 v[116:119], v[146:149], v[212:215], v[116:119]
	v_mfma_f32_16x16x32_bf16 v[84:87], v[154:157], v[212:215], v[84:87]
	v_mfma_f32_16x16x32_bf16 v[112:115], v[146:149], v[220:223], v[112:115]
	v_mfma_f32_16x16x32_bf16 v[80:83], v[154:157], v[220:223], v[80:83]
	v_mfma_f32_16x16x32_bf16 v[124:127], v[150:153], v[200:203], v[124:127]
	v_mfma_f32_16x16x32_bf16 v[92:95], v[158:161], v[200:203], v[92:95]
	v_mfma_f32_16x16x32_bf16 v[120:123], v[150:153], v[208:211], v[120:123]
	v_mfma_f32_16x16x32_bf16 v[88:91], v[158:161], v[208:211], v[88:91]
	v_mfma_f32_16x16x32_bf16 v[116:119], v[150:153], v[216:219], v[116:119]
	v_mfma_f32_16x16x32_bf16 v[84:87], v[158:161], v[216:219], v[84:87]
	v_mfma_f32_16x16x32_bf16 v[112:115], v[150:153], v[224:227], v[112:115]
	v_mfma_f32_16x16x32_bf16 v[80:83], v[158:161], v[224:227], v[80:83]
	s_setprio 0
	s_setprio 1
	v_mfma_f32_16x16x32_bf16 v[60:63], v[180:183], v[196:199], v[60:63]
	v_mfma_f32_16x16x32_bf16 v[28:31], v[188:191], v[196:199], v[28:31]
	v_mfma_f32_16x16x32_bf16 v[56:59], v[180:183], v[204:207], v[56:59]
	v_mfma_f32_16x16x32_bf16 v[24:27], v[188:191], v[204:207], v[24:27]
	v_mfma_f32_16x16x32_bf16 v[52:55], v[180:183], v[212:215], v[52:55]
	v_mfma_f32_16x16x32_bf16 v[20:23], v[188:191], v[212:215], v[20:23]
	v_mfma_f32_16x16x32_bf16 v[48:51], v[180:183], v[220:223], v[48:51]
	v_mfma_f32_16x16x32_bf16 v[16:19], v[188:191], v[220:223], v[16:19]
	v_mfma_f32_16x16x32_bf16 v[60:63], v[184:187], v[200:203], v[60:63]
	v_mfma_f32_16x16x32_bf16 v[28:31], v[192:195], v[200:203], v[28:31]
	v_mfma_f32_16x16x32_bf16 v[56:59], v[184:187], v[208:211], v[56:59]
	v_mfma_f32_16x16x32_bf16 v[24:27], v[192:195], v[208:211], v[24:27]
	v_mfma_f32_16x16x32_bf16 v[52:55], v[184:187], v[216:219], v[52:55]
	v_mfma_f32_16x16x32_bf16 v[20:23], v[192:195], v[216:219], v[20:23]
	v_mfma_f32_16x16x32_bf16 v[48:51], v[184:187], v[224:227], v[48:51]
	v_mfma_f32_16x16x32_bf16 v[16:19], v[192:195], v[224:227], v[16:19]
	s_barrier
; #define PG8_STAGE(bufoff, gbase, voff) do { _Pragma("unroll") for (int _i = 0; _i < 2; ++_i) \
;         __builtin_amdgcn_global_load_lds((const unsigned*)((const char*)(gbase) + (voff)[_i]), (LAS unsigned*)(lds + (bufoff) + ldsw + _i * 8192), 16, 0, 0); } while (0)
; #define PG8_LDA(dst, b, h) do { _Pragma("unroll") for (int m = 0; m < 4; ++m) _Pragma("unroll") for (int k = 0; k < 2; ++k) dst[m][k] = *(const LAS bf16x8*)(lds + PG8_SA(b, h) + aoff + m * 2048 + k * 1024); } while (0)
; #define PG8_MMA(ai, bj, At, Bt) do { __builtin_amdgcn_s_setprio(1); _Pragma("unroll") for (int m = 0; m < 4; ++m) _Pragma("unroll") for (int n = 0; n < 2; ++n) _Pragma("unroll") for (int k = 0; k < 2; ++k) \
;         acc[ai][bj][m][n] = __builtin_amdgcn_mfma_f32_16x16x32_bf16(Bt[n][k], At[m][k], acc[ai][bj][m][n], 0, 0, 0); __builtin_amdgcn_s_setprio(0); } while (0)
; #define PG8_WAIT_V(n) asm volatile("s_waitcnt vmcnt(" #n ")" ::: "memory")
; #define PG8_WAIT_L(n) asm volatile("s_waitcnt lgkmcnt(" #n ")" ::: "memory")
; #define PG8_BAR __builtin_amdgcn_s_barrier()
; #define PG8_SCHED __builtin_amdgcn_sched_barrier(0)
; template <class Epi, class Sched>
; __device__ __forceinline__ void gemm_phase(LAS unsigned char* lds, const int K, const Sched& S, const Epi& E) {
;     ...
;             PG8_LDA(At, 1, 1); PG8_STAGE(PG8_SB(1, 0), b3, voffB); PG8_STAGE(PG8_SB(1, 1), b3 + hstep, voffB); PG8_STAGE(PG8_SA(1, 0), a3, voffA);
;             PG8_WAIT_V(8); PG8_WAIT_L(0); PG8_BAR; PG8_MMA(1, 0, At, B0); PG8_MMA(1, 1, At, B1); PG8_BAR; PG8_SCHED;
;         }
;         if (wr == 0) PG8_BAR;
	s_setprio 0
	s_add_i32 s8, s12, s60
	v_lshl_add_u64 v[162:163], v[162:163], 0, s[36:37]
	s_mov_b32 m0, s8
	s_nop 0
	global_load_lds_dwordx4 v[162:163], off
	s_add_i32 m0, s8, 0x2000
	s_add_u32 s8, s54, 0xb0080
	v_lshl_add_u64 v[162:163], v[228:229], 0, s[36:37]
	s_addc_u32 s9, s55, 0
	s_add_i32 s12, s14, s60
	global_load_lds_dwordx4 v[162:163], off
	v_lshl_add_u64 v[162:163], s[8:9], 0, v[128:129]
	s_mov_b32 m0, s12
	s_nop 0
	global_load_lds_dwordx4 v[162:163], off
	v_lshl_add_u64 v[162:163], s[8:9], 0, v[138:139]
	s_add_i32 m0, s12, 0x2000
	s_nop 0
	global_load_lds_dwordx4 v[162:163], off
	v_lshl_add_u64 v[162:163], v[230:231], 0, s[36:37]
	s_mov_b32 m0, s68
	s_nop 0
	global_load_lds_dwordx4 v[162:163], off
	v_lshl_add_u64 v[162:163], v[232:233], 0, s[36:37]
	s_mov_b32 m0, s69
	s_nop 0
	global_load_lds_dwordx4 v[162:163], off
	ds_read_b128 v[196:199], v166 offset:49152
	ds_read_b128 v[200:203], v166 offset:50176
	ds_read_b128 v[204:207], v166 offset:51200
	ds_read_b128 v[208:211], v166 offset:52224
	ds_read_b128 v[212:215], v166 offset:53248
	ds_read_b128 v[216:219], v166 offset:54272
	ds_read_b128 v[220:223], v166 offset:55296
	ds_read_b128 v[224:227], v166 offset:56320
	s_waitcnt vmcnt(8)
	s_waitcnt lgkmcnt(0)
	s_setprio 1
	s_barrier
	v_mfma_f32_16x16x32_bf16 v[108:111], v[146:149], v[196:199], v[108:111]
	v_mfma_f32_16x16x32_bf16 v[76:79], v[154:157], v[196:199], v[76:79]
	v_mfma_f32_16x16x32_bf16 v[104:107], v[146:149], v[204:207], v[104:107]
	v_mfma_f32_16x16x32_bf16 v[72:75], v[154:157], v[204:207], v[72:75]
	v_mfma_f32_16x16x32_bf16 v[100:103], v[146:149], v[212:215], v[100:103]
	v_mfma_f32_16x16x32_bf16 v[68:71], v[154:157], v[212:215], v[68:71]
	v_mfma_f32_16x16x32_bf16 v[96:99], v[146:149], v[220:223], v[96:99]
	v_mfma_f32_16x16x32_bf16 v[64:67], v[154:157], v[220:223], v[64:67]
	v_mfma_f32_16x16x32_bf16 v[108:111], v[150:153], v[200:203], v[108:111]
	v_mfma_f32_16x16x32_bf16 v[76:79], v[158:161], v[200:203], v[76:79]
	v_mfma_f32_16x16x32_bf16 v[104:107], v[150:153], v[208:211], v[104:107]
	v_mfma_f32_16x16x32_bf16 v[72:75], v[158:161], v[208:211], v[72:75]
	v_mfma_f32_16x16x32_bf16 v[100:103], v[150:153], v[216:219], v[100:103]
	v_mfma_f32_16x16x32_bf16 v[68:71], v[158:161], v[216:219], v[68:71]
	v_mfma_f32_16x16x32_bf16 v[96:99], v[150:153], v[224:227], v[96:99]
	v_mfma_f32_16x16x32_bf16 v[64:67], v[158:161], v[224:227], v[64:67]
	s_setprio 0
	s_setprio 1
	v_mfma_f32_16x16x32_bf16 v[44:47], v[180:183], v[196:199], v[44:47]
	v_mfma_f32_16x16x32_bf16 v[12:15], v[188:191], v[196:199], v[12:15]
	v_mfma_f32_16x16x32_bf16 v[40:43], v[180:183], v[204:207], v[40:43]
	v_mfma_f32_16x16x32_bf16 v[8:11], v[188:191], v[204:207], v[8:11]
	v_mfma_f32_16x16x32_bf16 v[36:39], v[180:183], v[212:215], v[36:39]
	v_mfma_f32_16x16x32_bf16 v[4:7], v[188:191], v[212:215], v[4:7]
	v_mfma_f32_16x16x32_bf16 v[32:35], v[180:183], v[220:223], v[32:35]
	v_mfma_f32_16x16x32_bf16 v[0:3], v[188:191], v[220:223], v[0:3]
	v_mfma_f32_16x16x32_bf16 v[44:47], v[184:187], v[200:203], v[44:47]
	v_mfma_f32_16x16x32_bf16 v[12:15], v[192:195], v[200:203], v[12:15]
	v_mfma_f32_16x16x32_bf16 v[40:43], v[184:187], v[208:211], v[40:43]
	v_mfma_f32_16x16x32_bf16 v[8:11], v[192:195], v[208:211], v[8:11]
	v_mfma_f32_16x16x32_bf16 v[36:39], v[184:187], v[216:219], v[36:39]
	v_mfma_f32_16x16x32_bf16 v[4:7], v[192:195], v[216:219], v[4:7]
	v_mfma_f32_16x16x32_bf16 v[32:35], v[184:187], v[224:227], v[32:35]
	v_mfma_f32_16x16x32_bf16 v[0:3], v[192:195], v[224:227], v[0:3]
	s_barrier
	s_setprio 0
	s_add_u32 s10, s10, 0x100
	s_addc_u32 s11, s11, 0
	s_cmp_ge_i32 s13, s51
	s_mov_b64 s[8:9], s[52:53]
	s_mov_b32 s12, s13
	s_cbranch_scc0 .LBB0_1073
	s_and_b64 vcc, exec, s[40:41]
	s_cbranch_vccz .LBB0_1076
